# w_out GEMM epilogue: residual rows prefetched 2 rows ahead via hand-written src pointer calc; EpiHalf gate loads prefetched 14 deep
# speedup vs baseline: 1.0399x; 1.0098x over previous
.LBB0_697:
	s_add_u32 s34, vcc_lo, 0xfff80080
	s_addc_u32 s35, vcc_hi, -1
	s_add_i32 s84, 0, 0x10000
	v_add_u32_e32 v0, s84, v155
	ds_read_b128 v[146:149], v0
	ds_read_b128 v[150:153], v0 offset:1024
	ds_read_b128 v[158:161], v0 offset:2048
	ds_read_b128 v[162:165], v0 offset:3072
	s_cmp_eq_u32 s95, 28
	s_cselect_b32 s57, s1, s35
	s_cselect_b32 s56, s36, s34
	s_cselect_b32 s35, s31, s66
	s_cselect_b32 s34, s37, s51
	v_lshl_add_u64 v[170:171], vcc, 0, v[142:143]
	s_add_i32 m0, s2, 0xc000
	ds_read_b128 v[166:169], v157
	ds_read_b128 v[180:183], v157 offset:1024
	ds_read_b128 v[184:187], v157 offset:2048
	ds_read_b128 v[188:191], v157 offset:3072
	ds_read_b128 v[204:207], v157 offset:4096
	ds_read_b128 v[208:211], v157 offset:5120
	ds_read_b128 v[212:215], v157 offset:6144
	ds_read_b128 v[216:219], v157 offset:7168
	global_load_lds_dwordx4 v[170:171], off
	v_lshl_add_u64 v[170:171], vcc, 0, v[144:145]
	s_add_i32 m0, s2, 0xe000
	s_nop 0
	global_load_lds_dwordx4 v[170:171], off
	s_waitcnt lgkmcnt(8)
	s_barrier
	s_waitcnt lgkmcnt(0)
	s_setprio 1
	s_waitcnt lgkmcnt(0)
	v_mfma_f32_16x16x32_bf16 v[126:129], v[146:149], v[166:169], v[126:129]
	v_mfma_f32_16x16x32_bf16 v[122:125], v[158:161], v[166:169], v[122:125]
	v_mfma_f32_16x16x32_bf16 v[110:113], v[146:149], v[184:187], v[110:113]
	v_mfma_f32_16x16x32_bf16 v[106:109], v[158:161], v[184:187], v[106:109]
	v_mfma_f32_16x16x32_bf16 v[94:97], v[146:149], v[204:207], v[94:97]
	v_mfma_f32_16x16x32_bf16 v[90:93], v[158:161], v[204:207], v[90:93]
	v_mfma_f32_16x16x32_bf16 v[78:81], v[146:149], v[212:215], v[78:81]
	v_mfma_f32_16x16x32_bf16 v[74:77], v[158:161], v[212:215], v[74:77]
	v_mfma_f32_16x16x32_bf16 v[126:129], v[150:153], v[180:183], v[126:129]
	v_mfma_f32_16x16x32_bf16 v[122:125], v[162:165], v[180:183], v[122:125]
	v_mfma_f32_16x16x32_bf16 v[110:113], v[150:153], v[188:191], v[110:113]
	v_mfma_f32_16x16x32_bf16 v[106:109], v[162:165], v[188:191], v[106:109]
	v_mfma_f32_16x16x32_bf16 v[94:97], v[150:153], v[208:211], v[94:97]
	v_mfma_f32_16x16x32_bf16 v[90:93], v[162:165], v[208:211], v[90:93]
	v_mfma_f32_16x16x32_bf16 v[78:81], v[150:153], v[216:219], v[78:81]
	v_mfma_f32_16x16x32_bf16 v[74:77], v[162:165], v[216:219], v[74:77]
	s_setprio 0
	s_barrier
	s_add_i32 s86, 0, 0x14000
	s_add_i32 s84, s84, s97
	v_add_u32_e32 v0, s86, v155
	v_lshl_add_u64 v[170:171], s[34:35], 0, v[132:133]
	s_mov_b32 m0, s84
	ds_read_b128 v[220:223], v0
	ds_read_b128 v[224:227], v0 offset:1024
	ds_read_b128 v[228:231], v0 offset:2048
	ds_read_b128 v[232:235], v0 offset:3072
	global_load_lds_dwordx4 v[170:171], off
	v_lshl_add_u64 v[236:237], s[34:35], 0, v[136:137]
	s_add_i32 m0, s84, 0x2000
	s_nop 0
	global_load_lds_dwordx4 v[236:237], off
	s_barrier
	s_waitcnt lgkmcnt(0)
	s_setprio 1
	s_waitcnt lgkmcnt(0)
	v_mfma_f32_16x16x32_bf16 v[118:121], v[220:223], v[166:169], v[118:121]
	v_mfma_f32_16x16x32_bf16 v[114:117], v[228:231], v[166:169], v[114:117]
	v_mfma_f32_16x16x32_bf16 v[102:105], v[220:223], v[184:187], v[102:105]
	v_mfma_f32_16x16x32_bf16 v[98:101], v[228:231], v[184:187], v[98:101]
	v_mfma_f32_16x16x32_bf16 v[86:89], v[220:223], v[204:207], v[86:89]
	v_mfma_f32_16x16x32_bf16 v[82:85], v[228:231], v[204:207], v[82:85]
	v_mfma_f32_16x16x32_bf16 v[70:73], v[220:223], v[212:215], v[70:73]
	v_mfma_f32_16x16x32_bf16 v[66:69], v[228:231], v[212:215], v[66:69]
	v_mfma_f32_16x16x32_bf16 v[118:121], v[224:227], v[180:183], v[118:121]
	v_mfma_f32_16x16x32_bf16 v[114:117], v[232:235], v[180:183], v[114:117]
	v_mfma_f32_16x16x32_bf16 v[102:105], v[224:227], v[188:191], v[102:105]
	v_mfma_f32_16x16x32_bf16 v[98:101], v[232:235], v[188:191], v[98:101]
	v_mfma_f32_16x16x32_bf16 v[86:89], v[224:227], v[208:211], v[86:89]
	v_mfma_f32_16x16x32_bf16 v[82:85], v[232:235], v[208:211], v[82:85]
	v_mfma_f32_16x16x32_bf16 v[70:73], v[224:227], v[216:219], v[70:73]
	v_mfma_f32_16x16x32_bf16 v[66:69], v[232:235], v[216:219], v[66:69]
	s_setprio 0
	s_mov_b32 m0, s2
	v_lshl_add_u64 v[238:239], s[56:57], 0, v[130:131]
	s_barrier
	ds_read_b128 v[166:169], v157 offset:16384
	ds_read_b128 v[180:183], v157 offset:17408
	ds_read_b128 v[184:187], v157 offset:18432
	ds_read_b128 v[188:191], v157 offset:19456
	ds_read_b128 v[204:207], v157 offset:20480
	ds_read_b128 v[208:211], v157 offset:21504
	ds_read_b128 v[212:215], v157 offset:22528
	ds_read_b128 v[216:219], v157 offset:23552
	global_load_lds_dwordx4 v[238:239], off
	v_lshl_add_u64 v[240:241], s[56:57], 0, v[134:135]
	s_mov_b32 m0, s3
	s_nop 0
	global_load_lds_dwordx4 v[240:241], off
	s_barrier
	s_waitcnt lgkmcnt(0)
	s_setprio 1
	s_waitcnt lgkmcnt(0)
	v_mfma_f32_16x16x32_bf16 v[62:65], v[146:149], v[166:169], v[62:65]
	v_mfma_f32_16x16x32_bf16 v[58:61], v[158:161], v[166:169], v[58:61]
	v_mfma_f32_16x16x32_bf16 v[46:49], v[146:149], v[184:187], v[46:49]
	v_mfma_f32_16x16x32_bf16 v[42:45], v[158:161], v[184:187], v[42:45]
	v_mfma_f32_16x16x32_bf16 v[30:33], v[146:149], v[204:207], v[30:33]
	v_mfma_f32_16x16x32_bf16 v[26:29], v[158:161], v[204:207], v[26:29]
	v_mfma_f32_16x16x32_bf16 v[14:17], v[146:149], v[212:215], v[14:17]
	v_mfma_f32_16x16x32_bf16 v[10:13], v[158:161], v[212:215], v[10:13]
	v_mfma_f32_16x16x32_bf16 v[62:65], v[150:153], v[180:183], v[62:65]
	v_mfma_f32_16x16x32_bf16 v[58:61], v[162:165], v[180:183], v[58:61]
	v_mfma_f32_16x16x32_bf16 v[46:49], v[150:153], v[188:191], v[46:49]
	v_mfma_f32_16x16x32_bf16 v[42:45], v[162:165], v[188:191], v[42:45]
	v_mfma_f32_16x16x32_bf16 v[30:33], v[150:153], v[208:211], v[30:33]
	v_mfma_f32_16x16x32_bf16 v[26:29], v[162:165], v[208:211], v[26:29]
	v_mfma_f32_16x16x32_bf16 v[14:17], v[150:153], v[216:219], v[14:17]
	v_mfma_f32_16x16x32_bf16 v[10:13], v[162:165], v[216:219], v[10:13]
	s_setprio 0
	s_barrier
	s_add_u32 s84, s34, 0x80000
	s_addc_u32 s85, s35, 0
	s_add_i32 s86, s86, s97
	v_lshl_add_u64 v[146:147], s[84:85], 0, v[132:133]
	s_mov_b32 m0, s86
	s_nop 0
	global_load_lds_dwordx4 v[146:147], off
	v_lshl_add_u64 v[146:147], s[84:85], 0, v[136:137]
	s_add_i32 m0, s86, 0x2000
	s_nop 0
	global_load_lds_dwordx4 v[146:147], off
	s_waitcnt vmcnt(6)
	s_barrier
	s_setprio 1
	v_mfma_f32_16x16x32_bf16 v[54:57], v[220:223], v[166:169], v[54:57]
	v_mfma_f32_16x16x32_bf16 v[50:53], v[228:231], v[166:169], v[50:53]
	v_mfma_f32_16x16x32_bf16 v[38:41], v[220:223], v[184:187], v[38:41]
	v_mfma_f32_16x16x32_bf16 v[34:37], v[228:231], v[184:187], v[34:37]
	v_mfma_f32_16x16x32_bf16 v[22:25], v[220:223], v[204:207], v[22:25]
	v_mfma_f32_16x16x32_bf16 v[18:21], v[228:231], v[204:207], v[18:21]
	v_mfma_f32_16x16x32_bf16 v[6:9], v[220:223], v[212:215], v[6:9]
	v_mfma_f32_16x16x32_bf16 v[2:5], v[228:231], v[212:215], v[2:5]
	v_mfma_f32_16x16x32_bf16 v[54:57], v[224:227], v[180:183], v[54:57]
	v_mfma_f32_16x16x32_bf16 v[50:53], v[232:235], v[180:183], v[50:53]
	v_mfma_f32_16x16x32_bf16 v[38:41], v[224:227], v[188:191], v[38:41]
	v_mfma_f32_16x16x32_bf16 v[34:37], v[232:235], v[188:191], v[34:37]
	v_mfma_f32_16x16x32_bf16 v[22:25], v[224:227], v[208:211], v[22:25]
	v_mfma_f32_16x16x32_bf16 v[18:21], v[232:235], v[208:211], v[18:21]
	v_mfma_f32_16x16x32_bf16 v[6:9], v[224:227], v[216:219], v[6:9]
	v_mfma_f32_16x16x32_bf16 v[2:5], v[232:235], v[216:219], v[2:5]
	s_setprio 0
	s_add_i32 s84, 0, 0x18000
	v_add_u32_e32 v0, s84, v155
	s_barrier
	ds_read_b128 v[146:149], v0
	ds_read_b128 v[150:153], v0 offset:1024
	ds_read_b128 v[158:161], v0 offset:2048
	ds_read_b128 v[162:165], v0 offset:3072
	s_add_u32 s56, s56, 0x80000
	s_addc_u32 s57, s57, 0
	s_mov_b32 m0, s83
	v_lshl_add_u64 v[220:221], s[56:57], 0, v[130:131]
	ds_read_b128 v[166:169], v157 offset:32768
	ds_read_b128 v[180:183], v157 offset:33792
	ds_read_b128 v[184:187], v157 offset:34816
	ds_read_b128 v[188:191], v157 offset:35840
	ds_read_b128 v[204:207], v157 offset:36864
	ds_read_b128 v[208:211], v157 offset:37888
	ds_read_b128 v[212:215], v157 offset:38912
	ds_read_b128 v[216:219], v157 offset:39936
	global_load_lds_dwordx4 v[220:221], off
	v_lshl_add_u64 v[220:221], s[56:57], 0, v[134:135]
	s_mov_b32 m0, s70
	s_nop 0
	global_load_lds_dwordx4 v[220:221], off
	s_waitcnt lgkmcnt(8)
	s_barrier
	s_waitcnt lgkmcnt(0)
	s_setprio 1
	s_waitcnt lgkmcnt(0)
	v_mfma_f32_16x16x32_bf16 v[126:129], v[146:149], v[166:169], v[126:129]
	v_mfma_f32_16x16x32_bf16 v[122:125], v[158:161], v[166:169], v[122:125]
	v_mfma_f32_16x16x32_bf16 v[110:113], v[146:149], v[184:187], v[110:113]
	v_mfma_f32_16x16x32_bf16 v[106:109], v[158:161], v[184:187], v[106:109]
	v_mfma_f32_16x16x32_bf16 v[94:97], v[146:149], v[204:207], v[94:97]
	v_mfma_f32_16x16x32_bf16 v[90:93], v[158:161], v[204:207], v[90:93]
	v_mfma_f32_16x16x32_bf16 v[78:81], v[146:149], v[212:215], v[78:81]
	v_mfma_f32_16x16x32_bf16 v[74:77], v[158:161], v[212:215], v[74:77]
	v_mfma_f32_16x16x32_bf16 v[126:129], v[150:153], v[180:183], v[126:129]
	v_mfma_f32_16x16x32_bf16 v[122:125], v[162:165], v[180:183], v[122:125]
	v_mfma_f32_16x16x32_bf16 v[110:113], v[150:153], v[188:191], v[110:113]
	v_mfma_f32_16x16x32_bf16 v[106:109], v[162:165], v[188:191], v[106:109]
	v_mfma_f32_16x16x32_bf16 v[94:97], v[150:153], v[208:211], v[94:97]
	v_mfma_f32_16x16x32_bf16 v[90:93], v[162:165], v[208:211], v[90:93]
	v_mfma_f32_16x16x32_bf16 v[78:81], v[150:153], v[216:219], v[78:81]
	v_mfma_f32_16x16x32_bf16 v[74:77], v[162:165], v[216:219], v[74:77]
	s_setprio 0
	s_barrier
	s_add_i32 s56, 0, 0x1c000
	s_add_i32 s57, s84, s97
	v_add_u32_e32 v0, s56, v155
	v_lshl_add_u64 v[170:171], v[170:171], 0, s[48:49]
	s_mov_b32 m0, s57
	ds_read_b128 v[220:223], v0
	ds_read_b128 v[224:227], v0 offset:1024
	ds_read_b128 v[228:231], v0 offset:2048
	ds_read_b128 v[232:235], v0 offset:3072
	global_load_lds_dwordx4 v[170:171], off
	v_lshl_add_u64 v[170:171], v[236:237], 0, s[48:49]
	s_add_i32 m0, s57, 0x2000
	s_nop 0
	global_load_lds_dwordx4 v[170:171], off
	s_barrier
	s_waitcnt lgkmcnt(0)
	s_setprio 1
	s_waitcnt lgkmcnt(0)
	v_mfma_f32_16x16x32_bf16 v[118:121], v[220:223], v[166:169], v[118:121]
	v_mfma_f32_16x16x32_bf16 v[114:117], v[228:231], v[166:169], v[114:117]
	v_mfma_f32_16x16x32_bf16 v[102:105], v[220:223], v[184:187], v[102:105]
	v_mfma_f32_16x16x32_bf16 v[98:101], v[228:231], v[184:187], v[98:101]
	v_mfma_f32_16x16x32_bf16 v[86:89], v[220:223], v[204:207], v[86:89]
	v_mfma_f32_16x16x32_bf16 v[82:85], v[228:231], v[204:207], v[82:85]
	v_mfma_f32_16x16x32_bf16 v[70:73], v[220:223], v[212:215], v[70:73]
	v_mfma_f32_16x16x32_bf16 v[66:69], v[228:231], v[212:215], v[66:69]
	v_mfma_f32_16x16x32_bf16 v[118:121], v[224:227], v[180:183], v[118:121]
	v_mfma_f32_16x16x32_bf16 v[114:117], v[232:235], v[180:183], v[114:117]
	v_mfma_f32_16x16x32_bf16 v[102:105], v[224:227], v[188:191], v[102:105]
	v_mfma_f32_16x16x32_bf16 v[98:101], v[232:235], v[188:191], v[98:101]
	v_mfma_f32_16x16x32_bf16 v[86:89], v[224:227], v[208:211], v[86:89]
	v_mfma_f32_16x16x32_bf16 v[82:85], v[232:235], v[208:211], v[82:85]
	v_mfma_f32_16x16x32_bf16 v[70:73], v[224:227], v[216:219], v[70:73]
	v_mfma_f32_16x16x32_bf16 v[66:69], v[232:235], v[216:219], v[66:69]
	s_setprio 0
	s_mov_b32 m0, s74
	v_lshl_add_u64 v[170:171], v[238:239], 0, s[48:49]
	s_barrier
	ds_read_b128 v[166:169], v157 offset:49152
	ds_read_b128 v[180:183], v157 offset:50176
	ds_read_b128 v[184:187], v157 offset:51200
	ds_read_b128 v[188:191], v157 offset:52224
	ds_read_b128 v[204:207], v157 offset:53248
	ds_read_b128 v[208:211], v157 offset:54272
	ds_read_b128 v[212:215], v157 offset:55296
	ds_read_b128 v[216:219], v157 offset:56320
	global_load_lds_dwordx4 v[170:171], off
	v_lshl_add_u64 v[170:171], v[240:241], 0, s[48:49]
	s_mov_b32 m0, s75
	s_nop 0
	global_load_lds_dwordx4 v[170:171], off
	s_barrier
; __device__ __forceinline__ const float* row_src(const Params& p, int r) {
;     if (r < ROWS_P) { const int b = r / TP, t = r - b * TP;
;         if (t < PADR) return nullptr;
;         if (t < 128) return p.meta + (size_t)(t - PADR) * DM;
;         return p.x_prompt + ((size_t)b * 2048 + (t - 128)) * DM; }
;     return p.x_sample + (size_t)(r - ROWS_P) * DM;
; template <class Epi>
; __device__ __forceinline__ void gemm_phase(LAS unsigned char* lds, const GemmD g, const Epi& E) {
;     ...
;         for (int t = 0; t < nt; t += 2) PG8_KITER(t);
;     __device__ __forceinline__ void operator()(const f32x4 (&acc)[2][2][4][2], const Unit& u, int wr, int wc, int fr, int fq) const {
;         const int row0 = u.pm * BM + wr * 64 + fr, col0 = u.pn * BM + wc * 32 + 8 * fq;
; #pragma unroll
;         for (int ai = 0; ai < 2; ++ai)
; #pragma unroll
;             for (int m = 0; m < 4; ++m) { const int row = row0 + ai * HALF + m * 16;
;                 const float* src = row_src(p, row); float* dst = row_dst(p, row); float ss = 0.f;
;                 if (dst) {
; #pragma unroll
;                     for (int bj = 0; bj < 2; ++bj) { const int col = col0 + bj * HALF;
;                         const f32x4 h0 = __builtin_nontemporal_load((const f32x4*)(src + col)), h1 = __builtin_nontemporal_load((const f32x4*)(src + col + 4));
	s_waitcnt lgkmcnt(0)
	s_setprio 1
	s_waitcnt lgkmcnt(0)
	v_mfma_f32_16x16x32_bf16 v[62:65], v[146:149], v[166:169], v[62:65]
	v_mfma_f32_16x16x32_bf16 v[58:61], v[158:161], v[166:169], v[58:61]
	v_mfma_f32_16x16x32_bf16 v[46:49], v[146:149], v[184:187], v[46:49]
	v_mfma_f32_16x16x32_bf16 v[42:45], v[158:161], v[184:187], v[42:45]
	v_mfma_f32_16x16x32_bf16 v[30:33], v[146:149], v[204:207], v[30:33]
	v_mfma_f32_16x16x32_bf16 v[26:29], v[158:161], v[204:207], v[26:29]
	v_mfma_f32_16x16x32_bf16 v[14:17], v[146:149], v[212:215], v[14:17]
	v_mfma_f32_16x16x32_bf16 v[10:13], v[158:161], v[212:215], v[10:13]
	v_mfma_f32_16x16x32_bf16 v[62:65], v[150:153], v[180:183], v[62:65]
	v_mfma_f32_16x16x32_bf16 v[58:61], v[162:165], v[180:183], v[58:61]
	v_mfma_f32_16x16x32_bf16 v[46:49], v[150:153], v[188:191], v[46:49]
	v_mfma_f32_16x16x32_bf16 v[42:45], v[162:165], v[188:191], v[42:45]
	v_mfma_f32_16x16x32_bf16 v[30:33], v[150:153], v[208:211], v[30:33]
	v_mfma_f32_16x16x32_bf16 v[26:29], v[162:165], v[208:211], v[26:29]
	v_mfma_f32_16x16x32_bf16 v[14:17], v[150:153], v[216:219], v[14:17]
	v_mfma_f32_16x16x32_bf16 v[10:13], v[162:165], v[216:219], v[10:13]
	s_setprio 0
	s_barrier
	s_add_u32 s34, s34, 0x80080
	s_addc_u32 s35, s35, 0
	s_add_i32 s56, s56, s97
	v_lshl_add_u64 v[146:147], s[34:35], 0, v[132:133]
	s_mov_b32 m0, s56
	s_nop 0
	global_load_lds_dwordx4 v[146:147], off
	v_lshl_add_u64 v[146:147], s[34:35], 0, v[136:137]
	s_add_i32 m0, s56, 0x2000
	s_nop 0
	global_load_lds_dwordx4 v[146:147], off
	s_waitcnt vmcnt(6)
	s_barrier
	s_setprio 1
	v_mfma_f32_16x16x32_bf16 v[54:57], v[220:223], v[166:169], v[54:57]
	v_mfma_f32_16x16x32_bf16 v[50:53], v[228:231], v[166:169], v[50:53]
	v_mfma_f32_16x16x32_bf16 v[38:41], v[220:223], v[184:187], v[38:41]
	v_mfma_f32_16x16x32_bf16 v[34:37], v[228:231], v[184:187], v[34:37]
	v_mfma_f32_16x16x32_bf16 v[22:25], v[220:223], v[204:207], v[22:25]
	v_mfma_f32_16x16x32_bf16 v[18:21], v[228:231], v[204:207], v[18:21]
	v_mfma_f32_16x16x32_bf16 v[6:9], v[220:223], v[212:215], v[6:9]
	v_mfma_f32_16x16x32_bf16 v[2:5], v[228:231], v[212:215], v[2:5]
	v_mfma_f32_16x16x32_bf16 v[54:57], v[224:227], v[180:183], v[54:57]
	v_mfma_f32_16x16x32_bf16 v[50:53], v[232:235], v[180:183], v[50:53]
	v_mfma_f32_16x16x32_bf16 v[38:41], v[224:227], v[188:191], v[38:41]
	v_mfma_f32_16x16x32_bf16 v[34:37], v[232:235], v[188:191], v[34:37]
	v_mfma_f32_16x16x32_bf16 v[22:25], v[224:227], v[208:211], v[22:25]
	v_mfma_f32_16x16x32_bf16 v[18:21], v[232:235], v[208:211], v[18:21]
	v_mfma_f32_16x16x32_bf16 v[6:9], v[224:227], v[216:219], v[6:9]
	v_mfma_f32_16x16x32_bf16 v[2:5], v[232:235], v[216:219], v[2:5]
	s_setprio 0
	s_add_i32 s95, s95, 2
	s_add_u32 vcc_lo, vcc_lo, 0x100
	s_addc_u32 vcc_hi, vcc_hi, 0
	s_add_u32 s51, s51, 0x100
	s_addc_u32 s66, s66, 0
	s_cmp_gt_u32 s95, 29
	s_barrier
	s_cbranch_scc0 .LBB0_697
	v_lshl_add_u32 v148, s0, 8, v154
	v_readlane_b32 s4, v244, 12
	v_readlane_b32 s5, v244, 13
	v_readlane_b32 s6, v244, 14
	v_readlane_b32 s7, v244, 15
	v_readlane_b32 s12, v244, 22
	v_readlane_b32 s13, v244, 23
	v_lshl_or_b32 v190, s50, 8, v156
	v_mov_b32_e32 v191, 0
	v_mov_b32_e32 v188, 0x1000
	v_lshlrev_b32_e32 v190, 2, v190
	s_mov_b32 s8, 0xfff00000
	s_mov_b32 s9, -1
	s_mov_b32 s10, 0xfbc00000
	s_mov_b32 s11, -1
	v_lshl_add_u64 v[182:183], v[190:191], 0, s[4:5]
	v_lshl_add_u64 v[184:185], v[190:191], 0, s[6:7]
	v_lshl_add_u64 v[186:187], v[190:191], 0, s[12:13]
	v_lshl_add_u64 v[182:183], v[182:183], 0, s[8:9]
	v_lshl_add_u64 v[184:185], v[184:185], 0, s[10:11]
	v_mov_b32_e32 v238, v148
	v_mul_hi_i32 v239, v238, s90
	v_lshlrev_b32_e32 v241, 13, v238
	v_ashrrev_i32_e32 v239, 10, v239
	v_mul_i32_i24_e32 v240, 0xfffff780, v239
	v_lshlrev_b32_e32 v239, 24, v239
	v_add_u32_e32 v240, v240, v238
	v_cmp_gt_i32_e32 vcc, 0x2200, v238
	v_max_i32_e32 v238, 0x80, v240
	v_lshl_add_u32 v239, v238, 13, v239
	v_cndmask_b32_e32 v190, v241, v239, vcc
	v_cndmask_b32_e32 v236, v184, v182, vcc
	v_cndmask_b32_e32 v237, v185, v183, vcc
	v_cndmask_b32_e32 v240, v188, v240, vcc
	v_lshl_add_u64 v[236:237], v[190:191], 0, v[236:237]
	v_add_u32_e32 v190, 0xffffff90, v240
	v_cmp_gt_i32_e32 vcc, 0x80, v240
	v_max_i32_e32 v190, 0, v190
	v_lshlrev_b32_e32 v190, 13, v190
	v_lshl_add_u64 v[238:239], v[190:191], 0, v[186:187]
	v_cndmask_b32_e32 v236, v236, v238, vcc
	v_cndmask_b32_e32 v237, v237, v239, vcc
	global_load_dwordx4 v[204:207], v[236:237], off offset:16 nt
	global_load_dwordx4 v[208:211], v[236:237], off nt
	global_load_dwordx4 v[212:215], v[236:237], off offset:528 nt
	global_load_dwordx4 v[216:219], v[236:237], off offset:512 nt
	v_add_u32_e32 v238, 0x10, v148
	v_mul_hi_i32 v239, v238, s90
	v_lshlrev_b32_e32 v241, 13, v238
	v_ashrrev_i32_e32 v239, 10, v239
	v_mul_i32_i24_e32 v240, 0xfffff780, v239
	v_lshlrev_b32_e32 v239, 24, v239
	v_add_u32_e32 v240, v240, v238
	v_cmp_gt_i32_e32 vcc, 0x2200, v238
	v_max_i32_e32 v238, 0x80, v240
	v_lshl_add_u32 v239, v238, 13, v239
	v_cndmask_b32_e32 v190, v241, v239, vcc
	v_cndmask_b32_e32 v236, v184, v182, vcc
	v_cndmask_b32_e32 v237, v185, v183, vcc
	v_cndmask_b32_e32 v240, v188, v240, vcc
	v_lshl_add_u64 v[236:237], v[190:191], 0, v[236:237]
	v_add_u32_e32 v190, 0xffffff90, v240
	v_cmp_gt_i32_e32 vcc, 0x80, v240
	v_max_i32_e32 v190, 0, v190
	v_lshlrev_b32_e32 v190, 13, v190
	v_lshl_add_u64 v[238:239], v[190:191], 0, v[186:187]
	v_cndmask_b32_e32 v236, v236, v238, vcc
	v_cndmask_b32_e32 v237, v237, v239, vcc
	global_load_dwordx4 v[220:223], v[236:237], off offset:16 nt
	global_load_dwordx4 v[224:227], v[236:237], off nt
	global_load_dwordx4 v[228:231], v[236:237], off offset:528 nt
	global_load_dwordx4 v[232:235], v[236:237], off offset:512 nt
	s_movk_i32 s0, 0x21ff
	v_cmp_lt_i32_e32 vcc, s0, v148
	v_add_u32_e32 v146, 0xffffde00, v148
	s_and_saveexec_b64 s[0:1], vcc
	s_xor_b64 s[0:1], exec, s[0:1]
	s_cbranch_execz .LBB0_700
	v_mov_b32_e32 v147, v1
	v_readlane_b32 s4, v244, 12
	v_lshlrev_b64 v[150:151], 13, v[146:147]
	v_readlane_b32 s6, v244, 14
	v_readlane_b32 s7, v244, 15
	v_readlane_b32 s5, v244, 13
	v_readlane_b32 s8, v244, 16
	v_readlane_b32 s9, v244, 17
	v_readlane_b32 s10, v244, 18
	v_readlane_b32 s11, v244, 19
	v_readlane_b32 s12, v244, 20
	v_readlane_b32 s13, v244, 21
	v_readlane_b32 s14, v244, 22
	v_readlane_b32 s15, v244, 23
	v_readlane_b32 s16, v244, 24
	v_readlane_b32 s17, v244, 25
	v_readlane_b32 s18, v244, 26
	v_readlane_b32 s19, v244, 27
	v_lshl_add_u64 v[150:151], s[6:7], 0, v[150:151]

;     __device__ __forceinline__ void operator()(const f32x4 (&acc)[2][2][4][2], const Unit& u, int wr, int wc, int fr, int fq) const {
;     ...
;             for (int m = 0; m < 4; ++m) { const int row = row0 + ai * HALF + m * 16;
;                 const float* src = row_src(p, row); float* dst = row_dst(p, row); float ss = 0.f;
;                 if (dst) {
; #pragma unroll
;                     for (int bj = 0; bj < 2; ++bj) { const int col = col0 + bj * HALF;
;                         const f32x4 h0 = __builtin_nontemporal_load((const f32x4*)(src + col)), h1 = __builtin_nontemporal_load((const f32x4*)(src + col + 4));
;                         const f32x4 v0 = acc[ai][bj][m][0] + h0, v1 = acc[ai][bj][m][1] + h1;
;                         *(f32x4*)(dst + col) = v0; *(f32x4*)(dst + col + 4) = v1;
;                         ss += v0[0] * v0[0] + v0[1] * v0[1] + v0[2] * v0[2] + v0[3] * v0[3] + v1[0] * v1[0] + v1[1] * v1[1] + v1[2] * v1[2] + v1[3] * v1[3]; } }
;                 ss += __shfl_xor(ss, 16); ss += __shfl_xor(ss, 32);
;                 if (fq == 0) rss[(size_t)row * 32 + u.pn * 4 + wc] = ss; }
.LBB0_710:
	s_or_b64 exec, exec, s[0:1]
	v_lshl_or_b32 v146, s50, 8, v156
	v_cmp_ne_u64_e32 vcc, 0, v[152:153]
	v_mov_b32_e32 v0, 0
	v_ashrrev_i32_e32 v147, 31, v146
	s_and_saveexec_b64 s[0:1], vcc
	s_cbranch_execz .LBB0_712
	v_lshlrev_b64 v[166:167], 2, v[146:147]
	v_lshl_add_u64 v[168:169], v[150:151], 0, v[166:167]
	s_waitcnt vmcnt(4)
	v_mov_b32_e32 v158, v204
	v_mov_b32_e32 v159, v205
	v_mov_b32_e32 v160, v206
	v_mov_b32_e32 v161, v207
	v_mov_b32_e32 v162, v208
	v_mov_b32_e32 v163, v209
	v_mov_b32_e32 v164, v210
	v_mov_b32_e32 v165, v211
	v_pk_add_f32 v[124:125], v[124:125], v[160:161]
	v_pk_add_f32 v[128:129], v[128:129], v[164:165]
	v_pk_add_f32 v[126:127], v[126:127], v[162:163]
	v_lshl_add_u64 v[162:163], v[152:153], 0, v[166:167]
	v_pk_add_f32 v[122:123], v[122:123], v[158:159]
	global_store_dwordx4 v[162:163], v[126:129], off
	global_store_dwordx4 v[162:163], v[122:125], off offset:16
	v_mov_b32_e32 v150, v212
	v_mov_b32_e32 v151, v213
	v_mov_b32_e32 v152, v214
	v_mov_b32_e32 v153, v215
	v_mov_b32_e32 v158, v216
	v_mov_b32_e32 v159, v217
	v_mov_b32_e32 v160, v218
	v_mov_b32_e32 v161, v219
	v_pk_add_f32 v[116:117], v[116:117], v[152:153]
	v_pk_add_f32 v[120:121], v[120:121], v[160:161]
	v_pk_add_f32 v[118:119], v[118:119], v[158:159]
	v_pk_add_f32 v[114:115], v[114:115], v[150:151]
	global_store_dwordx4 v[162:163], v[118:121], off offset:512
	global_store_dwordx4 v[162:163], v[114:117], off offset:528
	v_mov_b32_e32 v151, v118
	v_mov_b32_e32 v118, v127
	v_mov_b32_e32 v150, v126
	v_pk_mul_f32 v[118:119], v[118:119], v[118:119]
	v_mov_b32_e32 v126, v128
	v_pk_fma_f32 v[118:119], v[150:151], v[150:151], v[118:119]
	v_mov_b32_e32 v127, v120
	v_pk_fma_f32 v[118:119], v[126:127], v[126:127], v[118:119]
	v_mov_b32_e32 v120, v129
	v_pk_fma_f32 v[118:119], v[120:121], v[120:121], v[118:119]
	v_mov_b32_e32 v120, v122
	v_mov_b32_e32 v121, v114
	v_pk_fma_f32 v[118:119], v[120:121], v[120:121], v[118:119]
	v_mov_b32_e32 v114, v123
	v_pk_fma_f32 v[114:115], v[114:115], v[114:115], v[118:119]
	v_mov_b32_e32 v118, v124
	v_mov_b32_e32 v119, v116
	v_pk_fma_f32 v[114:115], v[118:119], v[118:119], v[114:115]
	v_mov_b32_e32 v116, v125
	v_pk_fma_f32 v[114:115], v[116:117], v[116:117], v[114:115]
	s_nop 0
	v_add_f32_e32 v0, v114, v115
.LBB0_712:
	s_or_b64 exec, exec, s[0:1]
	v_add_u32_e32 v238, 0x20, v148
	v_mul_hi_i32 v239, v238, s90
	v_lshlrev_b32_e32 v241, 13, v238
	v_ashrrev_i32_e32 v239, 10, v239
	v_mul_i32_i24_e32 v240, 0xfffff780, v239
	v_lshlrev_b32_e32 v239, 24, v239
	v_add_u32_e32 v240, v240, v238
	v_cmp_gt_i32_e32 vcc, 0x2200, v238
	v_max_i32_e32 v238, 0x80, v240
	v_lshl_add_u32 v239, v238, 13, v239
	v_cndmask_b32_e32 v190, v241, v239, vcc
	v_cndmask_b32_e32 v236, v184, v182, vcc
	v_cndmask_b32_e32 v237, v185, v183, vcc
	v_cndmask_b32_e32 v240, v188, v240, vcc
	v_lshl_add_u64 v[236:237], v[190:191], 0, v[236:237]
	v_add_u32_e32 v190, 0xffffff90, v240
	v_cmp_gt_i32_e32 vcc, 0x80, v240
	v_max_i32_e32 v190, 0, v190
	v_lshlrev_b32_e32 v190, 13, v190
	v_lshl_add_u64 v[238:239], v[190:191], 0, v[186:187]
	v_cndmask_b32_e32 v236, v236, v238, vcc
	v_cndmask_b32_e32 v237, v237, v239, vcc
	global_load_dwordx4 v[204:207], v[236:237], off offset:16 nt
	global_load_dwordx4 v[208:211], v[236:237], off nt
	global_load_dwordx4 v[212:215], v[236:237], off offset:528 nt
	global_load_dwordx4 v[216:219], v[236:237], off offset:512 nt
	v_cmp_lt_i32_e32 vcc, v196, v194
	s_lshl_b32 s50, s50, 2
	s_ashr_i32 s51, s50, 31
	v_cndmask_b32_e32 v114, v193, v196, vcc
	v_lshlrev_b32_e32 v120, 2, v114
	ds_bpermute_b32 v114, v120, v0
	v_cmp_lt_i32_e32 vcc, v195, v194
	s_waitcnt lgkmcnt(0)
	v_add_f32_e32 v0, v0, v114
	v_cndmask_b32_e32 v115, v193, v195, vcc
	v_lshlrev_b32_e32 v121, 2, v115
	ds_bpermute_b32 v114, v121, v0
	s_and_saveexec_b64 s[0:1], s[38:39]
	s_cbranch_execz .LBB0_714
	v_ashrrev_i32_e32 v149, 31, v148
	v_lshlrev_b64 v[116:117], 7, v[148:149]
	v_lshl_add_u64 v[116:117], s[58:59], 0, v[116:117]
	v_lshl_add_u64 v[116:117], s[50:51], 2, v[116:117]
	s_lshl_b32 s66, s73, 2
	v_lshl_add_u64 v[116:117], v[116:117], 0, s[66:67]
	s_waitcnt lgkmcnt(0)
	v_add_f32_e32 v0, v0, v114
	global_store_dword v[116:117], v0, off

;     __device__ __forceinline__ void operator()(const f32x4 (&acc)[2][2][4][2], const Unit& u, int wr, int wc, int fr, int fq) const {
;     ...
;             for (int m = 0; m < 4; ++m) { const int row = row0 + ai * HALF + m * 16;
;                 const float* src = row_src(p, row); float* dst = row_dst(p, row); float ss = 0.f;
;                 if (dst) {
; #pragma unroll
;                     for (int bj = 0; bj < 2; ++bj) { const int col = col0 + bj * HALF;
;                         const f32x4 h0 = __builtin_nontemporal_load((const f32x4*)(src + col)), h1 = __builtin_nontemporal_load((const f32x4*)(src + col + 4));
;                         const f32x4 v0 = acc[ai][bj][m][0] + h0, v1 = acc[ai][bj][m][1] + h1;
;                         *(f32x4*)(dst + col) = v0; *(f32x4*)(dst + col + 4) = v1;
;                         ss += v0[0] * v0[0] + v0[1] * v0[1] + v0[2] * v0[2] + v0[3] * v0[3] + v1[0] * v1[0] + v1[1] * v1[1] + v1[2] * v1[2] + v1[3] * v1[3]; } }
;                 ss += __shfl_xor(ss, 16); ss += __shfl_xor(ss, 32);
;                 if (fq == 0) rss[(size_t)row * 32 + u.pn * 4 + wc] = ss; }
.LBB0_728:
	s_or_b64 exec, exec, s[0:1]
	v_cmp_ne_u64_e32 vcc, 0, v[118:119]
	v_mov_b32_e32 v0, 0
	s_and_saveexec_b64 s[0:1], vcc
	s_cbranch_execz .LBB0_730
	v_lshlrev_b64 v[150:151], 2, v[146:147]
	v_lshl_add_u64 v[152:153], v[116:117], 0, v[150:151]
	s_waitcnt vmcnt(4)
	v_mov_b32_e32 v122, v220
	v_mov_b32_e32 v123, v221
	v_mov_b32_e32 v124, v222
	v_mov_b32_e32 v125, v223
	v_mov_b32_e32 v126, v224
	v_mov_b32_e32 v127, v225
	v_mov_b32_e32 v128, v226
	v_mov_b32_e32 v129, v227
	v_pk_add_f32 v[108:109], v[108:109], v[124:125]
	v_pk_add_f32 v[112:113], v[112:113], v[128:129]
	v_pk_add_f32 v[110:111], v[110:111], v[126:127]
	v_lshl_add_u64 v[126:127], v[118:119], 0, v[150:151]
	v_pk_add_f32 v[106:107], v[106:107], v[122:123]
	global_store_dwordx4 v[126:127], v[110:113], off
	global_store_dwordx4 v[126:127], v[106:109], off offset:16
	v_mov_b32_e32 v116, v228
	v_mov_b32_e32 v117, v229
	v_mov_b32_e32 v118, v230
	v_mov_b32_e32 v119, v231
	v_mov_b32_e32 v122, v232
	v_mov_b32_e32 v123, v233
	v_mov_b32_e32 v124, v234
	v_mov_b32_e32 v125, v235
	v_pk_add_f32 v[100:101], v[100:101], v[118:119]
	v_pk_add_f32 v[104:105], v[104:105], v[124:125]
	v_pk_add_f32 v[102:103], v[102:103], v[122:123]
	v_pk_add_f32 v[98:99], v[98:99], v[116:117]
	global_store_dwordx4 v[126:127], v[102:105], off offset:512
	global_store_dwordx4 v[126:127], v[98:101], off offset:528
	v_mov_b32_e32 v117, v102
	v_mov_b32_e32 v102, v111
	v_mov_b32_e32 v116, v110
	v_pk_mul_f32 v[102:103], v[102:103], v[102:103]
	v_mov_b32_e32 v110, v112
	v_pk_fma_f32 v[102:103], v[116:117], v[116:117], v[102:103]
	v_mov_b32_e32 v111, v104
	v_pk_fma_f32 v[102:103], v[110:111], v[110:111], v[102:103]
	v_mov_b32_e32 v104, v113
	v_pk_fma_f32 v[102:103], v[104:105], v[104:105], v[102:103]
	v_mov_b32_e32 v104, v106
	v_mov_b32_e32 v105, v98
	v_pk_fma_f32 v[102:103], v[104:105], v[104:105], v[102:103]
	v_mov_b32_e32 v98, v107
	v_pk_fma_f32 v[98:99], v[98:99], v[98:99], v[102:103]
	v_mov_b32_e32 v102, v108
	v_mov_b32_e32 v103, v100
	v_pk_fma_f32 v[98:99], v[102:103], v[102:103], v[98:99]
	v_mov_b32_e32 v100, v109
	v_pk_fma_f32 v[98:99], v[100:101], v[100:101], v[98:99]
	s_nop 0
	v_add_f32_e32 v0, v98, v99
.LBB0_730:
	s_or_b64 exec, exec, s[0:1]
	v_add_u32_e32 v238, 0x30, v148
	v_mul_hi_i32 v239, v238, s90
	v_lshlrev_b32_e32 v241, 13, v238
	v_ashrrev_i32_e32 v239, 10, v239
	v_mul_i32_i24_e32 v240, 0xfffff780, v239
	v_lshlrev_b32_e32 v239, 24, v239
	v_add_u32_e32 v240, v240, v238
	v_cmp_gt_i32_e32 vcc, 0x2200, v238
	v_max_i32_e32 v238, 0x80, v240
	v_lshl_add_u32 v239, v238, 13, v239
	v_cndmask_b32_e32 v190, v241, v239, vcc
	v_cndmask_b32_e32 v236, v184, v182, vcc
	v_cndmask_b32_e32 v237, v185, v183, vcc
	v_cndmask_b32_e32 v240, v188, v240, vcc
	v_lshl_add_u64 v[236:237], v[190:191], 0, v[236:237]
	v_add_u32_e32 v190, 0xffffff90, v240
	v_cmp_gt_i32_e32 vcc, 0x80, v240
	v_max_i32_e32 v190, 0, v190
	v_lshlrev_b32_e32 v190, 13, v190
	v_lshl_add_u64 v[238:239], v[190:191], 0, v[186:187]
	v_cndmask_b32_e32 v236, v236, v238, vcc
	v_cndmask_b32_e32 v237, v237, v239, vcc
	global_load_dwordx4 v[220:223], v[236:237], off offset:16 nt
	global_load_dwordx4 v[224:227], v[236:237], off nt
	global_load_dwordx4 v[228:231], v[236:237], off offset:528 nt
	global_load_dwordx4 v[232:235], v[236:237], off offset:512 nt
	ds_bpermute_b32 v98, v120, v0
	s_waitcnt lgkmcnt(0)
	v_add_f32_e32 v0, v0, v98
	ds_bpermute_b32 v98, v121, v0
	s_and_saveexec_b64 s[0:1], s[38:39]
	s_cbranch_execz .LBB0_732
	v_ashrrev_i32_e32 v115, 31, v114
	v_lshlrev_b64 v[100:101], 7, v[114:115]
	v_lshl_add_u64 v[100:101], s[58:59], 0, v[100:101]
	v_lshl_add_u64 v[100:101], s[50:51], 2, v[100:101]
	s_lshl_b32 s66, s73, 2
	v_lshl_add_u64 v[100:101], v[100:101], 0, s[66:67]
	s_waitcnt lgkmcnt(0)
	v_add_f32_e32 v0, v0, v98
	global_store_dword v[100:101], v0, off

;     __device__ __forceinline__ void operator()(const f32x4 (&acc)[2][2][4][2], const Unit& u, int wr, int wc, int fr, int fq) const {
;     ...
;             for (int m = 0; m < 4; ++m) { const int row = row0 + ai * HALF + m * 16;
;                 const float* src = row_src(p, row); float* dst = row_dst(p, row); float ss = 0.f;
;                 if (dst) {
; #pragma unroll
;                     for (int bj = 0; bj < 2; ++bj) { const int col = col0 + bj * HALF;
;                         const f32x4 h0 = __builtin_nontemporal_load((const f32x4*)(src + col)), h1 = __builtin_nontemporal_load((const f32x4*)(src + col + 4));
;                         const f32x4 v0 = acc[ai][bj][m][0] + h0, v1 = acc[ai][bj][m][1] + h1;
;                         *(f32x4*)(dst + col) = v0; *(f32x4*)(dst + col + 4) = v1;
;                         ss += v0[0] * v0[0] + v0[1] * v0[1] + v0[2] * v0[2] + v0[3] * v0[3] + v1[0] * v1[0] + v1[1] * v1[1] + v1[2] * v1[2] + v1[3] * v1[3]; } }
;                 ss += __shfl_xor(ss, 16); ss += __shfl_xor(ss, 32);
;                 if (fq == 0) rss[(size_t)row * 32 + u.pn * 4 + wc] = ss; }
.LBB0_744:
	s_or_b64 exec, exec, s[0:1]
	v_cmp_ne_u64_e32 vcc, 0, v[102:103]
	v_mov_b32_e32 v0, 0
	s_and_saveexec_b64 s[0:1], vcc
	s_cbranch_execz .LBB0_746
	v_lshlrev_b64 v[112:113], 2, v[146:147]
	v_lshl_add_u64 v[114:115], v[100:101], 0, v[112:113]
	s_waitcnt vmcnt(4)
	v_mov_b32_e32 v104, v204
	v_mov_b32_e32 v105, v205
	v_mov_b32_e32 v106, v206
	v_mov_b32_e32 v107, v207
	v_mov_b32_e32 v108, v208
	v_mov_b32_e32 v109, v209
	v_mov_b32_e32 v110, v210
	v_mov_b32_e32 v111, v211
	v_pk_add_f32 v[92:93], v[92:93], v[106:107]
	v_pk_add_f32 v[96:97], v[96:97], v[110:111]
	v_pk_add_f32 v[94:95], v[94:95], v[108:109]
	v_lshl_add_u64 v[108:109], v[102:103], 0, v[112:113]
	v_pk_add_f32 v[90:91], v[90:91], v[104:105]
	global_store_dwordx4 v[108:109], v[94:97], off
	global_store_dwordx4 v[108:109], v[90:93], off offset:16
	v_mov_b32_e32 v100, v212
	v_mov_b32_e32 v101, v213
	v_mov_b32_e32 v102, v214
	v_mov_b32_e32 v103, v215
	v_mov_b32_e32 v104, v216
	v_mov_b32_e32 v105, v217
	v_mov_b32_e32 v106, v218
	v_mov_b32_e32 v107, v219
	v_pk_add_f32 v[84:85], v[84:85], v[102:103]
	v_pk_add_f32 v[88:89], v[88:89], v[106:107]
	v_pk_add_f32 v[86:87], v[86:87], v[104:105]
	v_pk_add_f32 v[82:83], v[82:83], v[100:101]
	global_store_dwordx4 v[108:109], v[86:89], off offset:512
	global_store_dwordx4 v[108:109], v[82:85], off offset:528
	v_mov_b32_e32 v101, v86
	v_mov_b32_e32 v86, v95
	v_mov_b32_e32 v100, v94
	v_pk_mul_f32 v[86:87], v[86:87], v[86:87]
	v_mov_b32_e32 v94, v96
	v_pk_fma_f32 v[86:87], v[100:101], v[100:101], v[86:87]
	v_mov_b32_e32 v95, v88
	v_pk_fma_f32 v[86:87], v[94:95], v[94:95], v[86:87]
	v_mov_b32_e32 v88, v97
	v_pk_fma_f32 v[86:87], v[88:89], v[88:89], v[86:87]
	v_mov_b32_e32 v88, v90
	v_mov_b32_e32 v89, v82
	v_pk_fma_f32 v[86:87], v[88:89], v[88:89], v[86:87]
	v_mov_b32_e32 v82, v91
	v_pk_fma_f32 v[82:83], v[82:83], v[82:83], v[86:87]
	v_mov_b32_e32 v86, v92
	v_mov_b32_e32 v87, v84
	v_pk_fma_f32 v[82:83], v[86:87], v[86:87], v[82:83]
	v_mov_b32_e32 v84, v93
	v_pk_fma_f32 v[82:83], v[84:85], v[84:85], v[82:83]
	s_nop 0
	v_add_f32_e32 v0, v82, v83
.LBB0_746:
	s_or_b64 exec, exec, s[0:1]
	v_add_u32_e32 v238, 0x80, v148
	v_mul_hi_i32 v239, v238, s90
	v_lshlrev_b32_e32 v241, 13, v238
	v_ashrrev_i32_e32 v239, 10, v239
	v_mul_i32_i24_e32 v240, 0xfffff780, v239
	v_lshlrev_b32_e32 v239, 24, v239
	v_add_u32_e32 v240, v240, v238
	v_cmp_gt_i32_e32 vcc, 0x2200, v238
	v_max_i32_e32 v238, 0x80, v240
	v_lshl_add_u32 v239, v238, 13, v239
	v_cndmask_b32_e32 v190, v241, v239, vcc
	v_cndmask_b32_e32 v236, v184, v182, vcc
	v_cndmask_b32_e32 v237, v185, v183, vcc
	v_cndmask_b32_e32 v240, v188, v240, vcc
	v_lshl_add_u64 v[236:237], v[190:191], 0, v[236:237]
	v_add_u32_e32 v190, 0xffffff90, v240
	v_cmp_gt_i32_e32 vcc, 0x80, v240
	v_max_i32_e32 v190, 0, v190
	v_lshlrev_b32_e32 v190, 13, v190
	v_lshl_add_u64 v[238:239], v[190:191], 0, v[186:187]
	v_cndmask_b32_e32 v236, v236, v238, vcc
	v_cndmask_b32_e32 v237, v237, v239, vcc
	global_load_dwordx4 v[204:207], v[236:237], off offset:16 nt
	global_load_dwordx4 v[208:211], v[236:237], off nt
	global_load_dwordx4 v[212:215], v[236:237], off offset:528 nt
	global_load_dwordx4 v[216:219], v[236:237], off offset:512 nt
	ds_bpermute_b32 v82, v120, v0
	s_waitcnt lgkmcnt(0)
	v_add_f32_e32 v0, v0, v82
	ds_bpermute_b32 v82, v121, v0
	s_and_saveexec_b64 s[0:1], s[38:39]
	s_cbranch_execz .LBB0_748
	v_ashrrev_i32_e32 v99, 31, v98
	v_lshlrev_b64 v[84:85], 7, v[98:99]
	v_lshl_add_u64 v[84:85], s[58:59], 0, v[84:85]
	v_lshl_add_u64 v[84:85], s[50:51], 2, v[84:85]
	s_lshl_b32 s66, s73, 2
	v_lshl_add_u64 v[84:85], v[84:85], 0, s[66:67]
	s_waitcnt lgkmcnt(0)
	v_add_f32_e32 v0, v0, v82
	global_store_dword v[84:85], v0, off

;     __device__ __forceinline__ void operator()(const f32x4 (&acc)[2][2][4][2], const Unit& u, int wr, int wc, int fr, int fq) const {
;     ...
;             for (int m = 0; m < 4; ++m) { const int row = row0 + ai * HALF + m * 16;
;                 const float* src = row_src(p, row); float* dst = row_dst(p, row); float ss = 0.f;
;                 if (dst) {
; #pragma unroll
;                     for (int bj = 0; bj < 2; ++bj) { const int col = col0 + bj * HALF;
;                         const f32x4 h0 = __builtin_nontemporal_load((const f32x4*)(src + col)), h1 = __builtin_nontemporal_load((const f32x4*)(src + col + 4));
;                         const f32x4 v0 = acc[ai][bj][m][0] + h0, v1 = acc[ai][bj][m][1] + h1;
;                         *(f32x4*)(dst + col) = v0; *(f32x4*)(dst + col + 4) = v1;
;                         ss += v0[0] * v0[0] + v0[1] * v0[1] + v0[2] * v0[2] + v0[3] * v0[3] + v1[0] * v1[0] + v1[1] * v1[1] + v1[2] * v1[2] + v1[3] * v1[3]; } }
;                 ss += __shfl_xor(ss, 16); ss += __shfl_xor(ss, 32);
;                 if (fq == 0) rss[(size_t)row * 32 + u.pn * 4 + wc] = ss; }
.LBB0_762:
	s_or_b64 exec, exec, s[0:1]
	v_cmp_ne_u64_e32 vcc, 0, v[86:87]
	v_mov_b32_e32 v0, 0
	s_and_saveexec_b64 s[0:1], vcc
	s_cbranch_execz .LBB0_764
	v_lshlrev_b64 v[96:97], 2, v[146:147]
	v_lshl_add_u64 v[98:99], v[84:85], 0, v[96:97]
	s_waitcnt vmcnt(4)
	v_mov_b32_e32 v88, v220
	v_mov_b32_e32 v89, v221
	v_mov_b32_e32 v90, v222
	v_mov_b32_e32 v91, v223
	v_mov_b32_e32 v92, v224
	v_mov_b32_e32 v93, v225
	v_mov_b32_e32 v94, v226
	v_mov_b32_e32 v95, v227
	v_pk_add_f32 v[76:77], v[76:77], v[90:91]
	v_pk_add_f32 v[80:81], v[80:81], v[94:95]
	v_pk_add_f32 v[78:79], v[78:79], v[92:93]
	v_lshl_add_u64 v[92:93], v[86:87], 0, v[96:97]
	v_pk_add_f32 v[74:75], v[74:75], v[88:89]
	global_store_dwordx4 v[92:93], v[78:81], off
	global_store_dwordx4 v[92:93], v[74:77], off offset:16
	v_mov_b32_e32 v84, v228
	v_mov_b32_e32 v85, v229
	v_mov_b32_e32 v86, v230
	v_mov_b32_e32 v87, v231
	v_mov_b32_e32 v88, v232
	v_mov_b32_e32 v89, v233
	v_mov_b32_e32 v90, v234
	v_mov_b32_e32 v91, v235
	v_pk_add_f32 v[68:69], v[68:69], v[86:87]
	v_pk_add_f32 v[72:73], v[72:73], v[90:91]
	v_pk_add_f32 v[70:71], v[70:71], v[88:89]
	v_pk_add_f32 v[66:67], v[66:67], v[84:85]
	global_store_dwordx4 v[92:93], v[70:73], off offset:512
	global_store_dwordx4 v[92:93], v[66:69], off offset:528
	v_mov_b32_e32 v85, v70
	v_mov_b32_e32 v70, v79
	v_mov_b32_e32 v84, v78
	v_pk_mul_f32 v[70:71], v[70:71], v[70:71]
	v_mov_b32_e32 v78, v80
	v_pk_fma_f32 v[70:71], v[84:85], v[84:85], v[70:71]
	v_mov_b32_e32 v79, v72
	v_pk_fma_f32 v[70:71], v[78:79], v[78:79], v[70:71]
	v_mov_b32_e32 v72, v81
	v_pk_fma_f32 v[70:71], v[72:73], v[72:73], v[70:71]
	v_mov_b32_e32 v72, v74
	v_mov_b32_e32 v73, v66
	v_pk_fma_f32 v[70:71], v[72:73], v[72:73], v[70:71]
	v_mov_b32_e32 v66, v75
	v_pk_fma_f32 v[66:67], v[66:67], v[66:67], v[70:71]
	v_mov_b32_e32 v70, v76
	v_mov_b32_e32 v71, v68
	v_pk_fma_f32 v[66:67], v[70:71], v[70:71], v[66:67]
	v_mov_b32_e32 v68, v77
	v_pk_fma_f32 v[66:67], v[68:69], v[68:69], v[66:67]
	s_nop 0
	v_add_f32_e32 v0, v66, v67
.LBB0_764:
	s_or_b64 exec, exec, s[0:1]
	v_add_u32_e32 v238, 0x90, v148
	v_mul_hi_i32 v239, v238, s90
	v_lshlrev_b32_e32 v241, 13, v238
	v_ashrrev_i32_e32 v239, 10, v239
	v_mul_i32_i24_e32 v240, 0xfffff780, v239
	v_lshlrev_b32_e32 v239, 24, v239
	v_add_u32_e32 v240, v240, v238
	v_cmp_gt_i32_e32 vcc, 0x2200, v238
	v_max_i32_e32 v238, 0x80, v240
	v_lshl_add_u32 v239, v238, 13, v239
	v_cndmask_b32_e32 v190, v241, v239, vcc
	v_cndmask_b32_e32 v236, v184, v182, vcc
	v_cndmask_b32_e32 v237, v185, v183, vcc
	v_cndmask_b32_e32 v240, v188, v240, vcc
	v_lshl_add_u64 v[236:237], v[190:191], 0, v[236:237]
	v_add_u32_e32 v190, 0xffffff90, v240
	v_cmp_gt_i32_e32 vcc, 0x80, v240
	v_max_i32_e32 v190, 0, v190
	v_lshlrev_b32_e32 v190, 13, v190
	v_lshl_add_u64 v[238:239], v[190:191], 0, v[186:187]
	v_cndmask_b32_e32 v236, v236, v238, vcc
	v_cndmask_b32_e32 v237, v237, v239, vcc
	global_load_dwordx4 v[220:223], v[236:237], off offset:16 nt
	global_load_dwordx4 v[224:227], v[236:237], off nt
	global_load_dwordx4 v[228:231], v[236:237], off offset:528 nt
	global_load_dwordx4 v[232:235], v[236:237], off offset:512 nt
	ds_bpermute_b32 v66, v120, v0
	s_waitcnt lgkmcnt(0)
	v_add_f32_e32 v0, v0, v66
	ds_bpermute_b32 v66, v121, v0
	s_and_saveexec_b64 s[0:1], s[38:39]
	s_cbranch_execz .LBB0_766
	v_ashrrev_i32_e32 v83, 31, v82
	v_lshlrev_b64 v[68:69], 7, v[82:83]
	v_lshl_add_u64 v[68:69], s[58:59], 0, v[68:69]
	v_lshl_add_u64 v[68:69], s[50:51], 2, v[68:69]
	s_lshl_b32 s66, s73, 2
	v_lshl_add_u64 v[68:69], v[68:69], 0, s[66:67]
	s_waitcnt lgkmcnt(0)
	v_add_f32_e32 v0, v0, v66
	global_store_dword v[68:69], v0, off

;     __device__ __forceinline__ void operator()(const f32x4 (&acc)[2][2][4][2], const Unit& u, int wr, int wc, int fr, int fq) const {
;     ...
;             for (int m = 0; m < 4; ++m) { const int row = row0 + ai * HALF + m * 16;
;                 const float* src = row_src(p, row); float* dst = row_dst(p, row); float ss = 0.f;
;                 if (dst) {
; #pragma unroll
;                     for (int bj = 0; bj < 2; ++bj) { const int col = col0 + bj * HALF;
;                         const f32x4 h0 = __builtin_nontemporal_load((const f32x4*)(src + col)), h1 = __builtin_nontemporal_load((const f32x4*)(src + col + 4));
;                         const f32x4 v0 = acc[ai][bj][m][0] + h0, v1 = acc[ai][bj][m][1] + h1;
;                         *(f32x4*)(dst + col) = v0; *(f32x4*)(dst + col + 4) = v1;
;                         ss += v0[0] * v0[0] + v0[1] * v0[1] + v0[2] * v0[2] + v0[3] * v0[3] + v1[0] * v1[0] + v1[1] * v1[1] + v1[2] * v1[2] + v1[3] * v1[3]; } }
;                 ss += __shfl_xor(ss, 16); ss += __shfl_xor(ss, 32);
;                 if (fq == 0) rss[(size_t)row * 32 + u.pn * 4 + wc] = ss; }
.LBB0_778:
	s_or_b64 exec, exec, s[0:1]
	v_cmp_ne_u64_e32 vcc, 0, v[70:71]
	v_mov_b32_e32 v0, 0
	s_and_saveexec_b64 s[0:1], vcc
	s_cbranch_execz .LBB0_780
	v_lshlrev_b64 v[80:81], 2, v[146:147]
	v_lshl_add_u64 v[82:83], v[68:69], 0, v[80:81]
	s_waitcnt vmcnt(4)
	v_mov_b32_e32 v72, v204
	v_mov_b32_e32 v73, v205
	v_mov_b32_e32 v74, v206
	v_mov_b32_e32 v75, v207
	v_mov_b32_e32 v76, v208
	v_mov_b32_e32 v77, v209
	v_mov_b32_e32 v78, v210
	v_mov_b32_e32 v79, v211
	v_pk_add_f32 v[60:61], v[60:61], v[74:75]
	v_pk_add_f32 v[64:65], v[64:65], v[78:79]
	v_pk_add_f32 v[62:63], v[62:63], v[76:77]
	v_lshl_add_u64 v[76:77], v[70:71], 0, v[80:81]
	v_pk_add_f32 v[58:59], v[58:59], v[72:73]
	global_store_dwordx4 v[76:77], v[62:65], off
	global_store_dwordx4 v[76:77], v[58:61], off offset:16
	v_mov_b32_e32 v68, v212
	v_mov_b32_e32 v69, v213
	v_mov_b32_e32 v70, v214
	v_mov_b32_e32 v71, v215
	v_mov_b32_e32 v72, v216
	v_mov_b32_e32 v73, v217
	v_mov_b32_e32 v74, v218
	v_mov_b32_e32 v75, v219
	v_pk_add_f32 v[52:53], v[52:53], v[70:71]
	v_pk_add_f32 v[56:57], v[56:57], v[74:75]
	v_pk_add_f32 v[54:55], v[54:55], v[72:73]
	v_pk_add_f32 v[50:51], v[50:51], v[68:69]
	global_store_dwordx4 v[76:77], v[54:57], off offset:512
	global_store_dwordx4 v[76:77], v[50:53], off offset:528
	v_mov_b32_e32 v69, v54
	v_mov_b32_e32 v54, v63
	v_mov_b32_e32 v68, v62
	v_pk_mul_f32 v[54:55], v[54:55], v[54:55]
	v_mov_b32_e32 v62, v64
	v_pk_fma_f32 v[54:55], v[68:69], v[68:69], v[54:55]
	v_mov_b32_e32 v63, v56
	v_pk_fma_f32 v[54:55], v[62:63], v[62:63], v[54:55]
	v_mov_b32_e32 v56, v65
	v_pk_fma_f32 v[54:55], v[56:57], v[56:57], v[54:55]
	v_mov_b32_e32 v56, v58
	v_mov_b32_e32 v57, v50
	v_pk_fma_f32 v[54:55], v[56:57], v[56:57], v[54:55]
	v_mov_b32_e32 v50, v59
	v_pk_fma_f32 v[50:51], v[50:51], v[50:51], v[54:55]
	v_mov_b32_e32 v54, v60
	v_mov_b32_e32 v55, v52
	v_pk_fma_f32 v[50:51], v[54:55], v[54:55], v[50:51]
	v_mov_b32_e32 v52, v61
	v_pk_fma_f32 v[50:51], v[52:53], v[52:53], v[50:51]
	s_nop 0
	v_add_f32_e32 v0, v50, v51
.LBB0_780:
	s_or_b64 exec, exec, s[0:1]
	v_add_u32_e32 v238, 0xa0, v148
	v_mul_hi_i32 v239, v238, s90
	v_lshlrev_b32_e32 v241, 13, v238
	v_ashrrev_i32_e32 v239, 10, v239
	v_mul_i32_i24_e32 v240, 0xfffff780, v239
	v_lshlrev_b32_e32 v239, 24, v239
	v_add_u32_e32 v240, v240, v238
	v_cmp_gt_i32_e32 vcc, 0x2200, v238
	v_max_i32_e32 v238, 0x80, v240
	v_lshl_add_u32 v239, v238, 13, v239
	v_cndmask_b32_e32 v190, v241, v239, vcc
	v_cndmask_b32_e32 v236, v184, v182, vcc
	v_cndmask_b32_e32 v237, v185, v183, vcc
	v_cndmask_b32_e32 v240, v188, v240, vcc
	v_lshl_add_u64 v[236:237], v[190:191], 0, v[236:237]
	v_add_u32_e32 v190, 0xffffff90, v240
	v_cmp_gt_i32_e32 vcc, 0x80, v240
	v_max_i32_e32 v190, 0, v190
	v_lshlrev_b32_e32 v190, 13, v190
	v_lshl_add_u64 v[238:239], v[190:191], 0, v[186:187]
	v_cndmask_b32_e32 v236, v236, v238, vcc
	v_cndmask_b32_e32 v237, v237, v239, vcc
	global_load_dwordx4 v[204:207], v[236:237], off offset:16 nt
	global_load_dwordx4 v[208:211], v[236:237], off nt
	global_load_dwordx4 v[212:215], v[236:237], off offset:528 nt
	global_load_dwordx4 v[216:219], v[236:237], off offset:512 nt
	ds_bpermute_b32 v50, v120, v0
	s_waitcnt lgkmcnt(0)
	v_add_f32_e32 v0, v0, v50
	ds_bpermute_b32 v50, v121, v0
	s_and_saveexec_b64 s[0:1], s[38:39]
	s_cbranch_execz .LBB0_782
	v_ashrrev_i32_e32 v67, 31, v66
	v_lshlrev_b64 v[52:53], 7, v[66:67]
	v_lshl_add_u64 v[52:53], s[58:59], 0, v[52:53]
	v_lshl_add_u64 v[52:53], s[50:51], 2, v[52:53]
	s_lshl_b32 s66, s73, 2
	v_lshl_add_u64 v[52:53], v[52:53], 0, s[66:67]
	s_waitcnt lgkmcnt(0)
	v_add_f32_e32 v0, v0, v50
	global_store_dword v[52:53], v0, off

;     __device__ __forceinline__ void operator()(const f32x4 (&acc)[2][2][4][2], const Unit& u, int wr, int wc, int fr, int fq) const {
;     ...
;             for (int m = 0; m < 4; ++m) { const int row = row0 + ai * HALF + m * 16;
;                 const float* src = row_src(p, row); float* dst = row_dst(p, row); float ss = 0.f;
;                 if (dst) {
; #pragma unroll
;                     for (int bj = 0; bj < 2; ++bj) { const int col = col0 + bj * HALF;
;                         const f32x4 h0 = __builtin_nontemporal_load((const f32x4*)(src + col)), h1 = __builtin_nontemporal_load((const f32x4*)(src + col + 4));
;                         const f32x4 v0 = acc[ai][bj][m][0] + h0, v1 = acc[ai][bj][m][1] + h1;
;                         *(f32x4*)(dst + col) = v0; *(f32x4*)(dst + col + 4) = v1;
;                         ss += v0[0] * v0[0] + v0[1] * v0[1] + v0[2] * v0[2] + v0[3] * v0[3] + v1[0] * v1[0] + v1[1] * v1[1] + v1[2] * v1[2] + v1[3] * v1[3]; } }
;                 ss += __shfl_xor(ss, 16); ss += __shfl_xor(ss, 32);
;                 if (fq == 0) rss[(size_t)row * 32 + u.pn * 4 + wc] = ss; }
.LBB0_796:
	s_or_b64 exec, exec, s[0:1]
	v_cmp_ne_u64_e32 vcc, 0, v[54:55]
	v_mov_b32_e32 v0, 0
	s_and_saveexec_b64 s[0:1], vcc
	s_cbranch_execz .LBB0_798
	v_lshlrev_b64 v[64:65], 2, v[146:147]
	v_lshl_add_u64 v[66:67], v[52:53], 0, v[64:65]
	s_waitcnt vmcnt(4)
	v_mov_b32_e32 v56, v220
	v_mov_b32_e32 v57, v221
	v_mov_b32_e32 v58, v222
	v_mov_b32_e32 v59, v223
	v_mov_b32_e32 v60, v224
	v_mov_b32_e32 v61, v225
	v_mov_b32_e32 v62, v226
	v_mov_b32_e32 v63, v227
	v_pk_add_f32 v[44:45], v[44:45], v[58:59]
	v_pk_add_f32 v[48:49], v[48:49], v[62:63]
	v_pk_add_f32 v[46:47], v[46:47], v[60:61]
	v_lshl_add_u64 v[60:61], v[54:55], 0, v[64:65]
	v_pk_add_f32 v[42:43], v[42:43], v[56:57]
	global_store_dwordx4 v[60:61], v[46:49], off
	global_store_dwordx4 v[60:61], v[42:45], off offset:16
	v_mov_b32_e32 v52, v228
	v_mov_b32_e32 v53, v229
	v_mov_b32_e32 v54, v230
	v_mov_b32_e32 v55, v231
	v_mov_b32_e32 v56, v232
	v_mov_b32_e32 v57, v233
	v_mov_b32_e32 v58, v234
	v_mov_b32_e32 v59, v235
	v_pk_add_f32 v[36:37], v[36:37], v[54:55]
	v_pk_add_f32 v[40:41], v[40:41], v[58:59]
	v_pk_add_f32 v[38:39], v[38:39], v[56:57]
	v_pk_add_f32 v[34:35], v[34:35], v[52:53]
	global_store_dwordx4 v[60:61], v[38:41], off offset:512
	global_store_dwordx4 v[60:61], v[34:37], off offset:528
	v_mov_b32_e32 v53, v38
	v_mov_b32_e32 v38, v47
	v_mov_b32_e32 v52, v46
	v_pk_mul_f32 v[38:39], v[38:39], v[38:39]
	v_mov_b32_e32 v46, v48
	v_pk_fma_f32 v[38:39], v[52:53], v[52:53], v[38:39]
	v_mov_b32_e32 v47, v40
	v_pk_fma_f32 v[38:39], v[46:47], v[46:47], v[38:39]
	v_mov_b32_e32 v40, v49
	v_pk_fma_f32 v[38:39], v[40:41], v[40:41], v[38:39]
	v_mov_b32_e32 v40, v42
	v_mov_b32_e32 v41, v34
	v_pk_fma_f32 v[38:39], v[40:41], v[40:41], v[38:39]
	v_mov_b32_e32 v34, v43
	v_pk_fma_f32 v[34:35], v[34:35], v[34:35], v[38:39]
	v_mov_b32_e32 v38, v44
	v_mov_b32_e32 v39, v36
	v_pk_fma_f32 v[34:35], v[38:39], v[38:39], v[34:35]
	v_mov_b32_e32 v36, v45
	v_pk_fma_f32 v[34:35], v[36:37], v[36:37], v[34:35]
	s_nop 0
	v_add_f32_e32 v0, v34, v35
.LBB0_798:
	s_or_b64 exec, exec, s[0:1]
	v_add_u32_e32 v238, 0xb0, v148
	v_mul_hi_i32 v239, v238, s90
	v_lshlrev_b32_e32 v241, 13, v238
	v_ashrrev_i32_e32 v239, 10, v239
	v_mul_i32_i24_e32 v240, 0xfffff780, v239
	v_lshlrev_b32_e32 v239, 24, v239
	v_add_u32_e32 v240, v240, v238
	v_cmp_gt_i32_e32 vcc, 0x2200, v238
	v_max_i32_e32 v238, 0x80, v240
	v_lshl_add_u32 v239, v238, 13, v239
	v_cndmask_b32_e32 v190, v241, v239, vcc
	v_cndmask_b32_e32 v236, v184, v182, vcc
	v_cndmask_b32_e32 v237, v185, v183, vcc
	v_cndmask_b32_e32 v240, v188, v240, vcc
	v_lshl_add_u64 v[236:237], v[190:191], 0, v[236:237]
	v_add_u32_e32 v190, 0xffffff90, v240
	v_cmp_gt_i32_e32 vcc, 0x80, v240
	v_max_i32_e32 v190, 0, v190
	v_lshlrev_b32_e32 v190, 13, v190
	v_lshl_add_u64 v[238:239], v[190:191], 0, v[186:187]
	v_cndmask_b32_e32 v236, v236, v238, vcc
	v_cndmask_b32_e32 v237, v237, v239, vcc
	global_load_dwordx4 v[220:223], v[236:237], off offset:16 nt
	global_load_dwordx4 v[224:227], v[236:237], off nt
	global_load_dwordx4 v[228:231], v[236:237], off offset:528 nt
	global_load_dwordx4 v[232:235], v[236:237], off offset:512 nt
	ds_bpermute_b32 v34, v120, v0
	s_waitcnt lgkmcnt(0)
	v_add_f32_e32 v0, v0, v34
	ds_bpermute_b32 v34, v121, v0
	s_and_saveexec_b64 s[0:1], s[38:39]
	s_cbranch_execz .LBB0_800
	v_ashrrev_i32_e32 v51, 31, v50
	v_lshlrev_b64 v[36:37], 7, v[50:51]
	v_lshl_add_u64 v[36:37], s[58:59], 0, v[36:37]
	v_lshl_add_u64 v[36:37], s[50:51], 2, v[36:37]
	s_lshl_b32 s66, s73, 2
	v_lshl_add_u64 v[36:37], v[36:37], 0, s[66:67]
	s_waitcnt lgkmcnt(0)
	v_add_f32_e32 v0, v0, v34
	global_store_dword v[36:37], v0, off

;     __device__ __forceinline__ void operator()(const f32x4 (&acc)[2][2][4][2], const Unit& u, int wr, int wc, int fr, int fq) const {
;     ...
;             for (int m = 0; m < 4; ++m) { const int row = row0 + ai * HALF + m * 16;
;                 const float* src = row_src(p, row); float* dst = row_dst(p, row); float ss = 0.f;
;                 if (dst) {
; #pragma unroll
;                     for (int bj = 0; bj < 2; ++bj) { const int col = col0 + bj * HALF;
;                         const f32x4 h0 = __builtin_nontemporal_load((const f32x4*)(src + col)), h1 = __builtin_nontemporal_load((const f32x4*)(src + col + 4));
;                         const f32x4 v0 = acc[ai][bj][m][0] + h0, v1 = acc[ai][bj][m][1] + h1;
;                         *(f32x4*)(dst + col) = v0; *(f32x4*)(dst + col + 4) = v1;
;                         ss += v0[0] * v0[0] + v0[1] * v0[1] + v0[2] * v0[2] + v0[3] * v0[3] + v1[0] * v1[0] + v1[1] * v1[1] + v1[2] * v1[2] + v1[3] * v1[3]; } }
;                 ss += __shfl_xor(ss, 16); ss += __shfl_xor(ss, 32);
;                 if (fq == 0) rss[(size_t)row * 32 + u.pn * 4 + wc] = ss; }
.LBB0_814:
	s_or_b64 exec, exec, s[0:1]
	v_cmp_ne_u64_e32 vcc, 0, v[38:39]
	v_mov_b32_e32 v0, 0
	s_and_saveexec_b64 s[0:1], vcc
	s_cbranch_execz .LBB0_816
	v_lshlrev_b64 v[48:49], 2, v[146:147]
	v_lshl_add_u64 v[50:51], v[36:37], 0, v[48:49]
	s_waitcnt vmcnt(4)
	v_mov_b32_e32 v40, v204
	v_mov_b32_e32 v41, v205
	v_mov_b32_e32 v42, v206
	v_mov_b32_e32 v43, v207
	v_mov_b32_e32 v44, v208
	v_mov_b32_e32 v45, v209
	v_mov_b32_e32 v46, v210
	v_mov_b32_e32 v47, v211
	v_pk_add_f32 v[28:29], v[28:29], v[42:43]
	v_pk_add_f32 v[32:33], v[32:33], v[46:47]
	v_pk_add_f32 v[30:31], v[30:31], v[44:45]
	v_lshl_add_u64 v[44:45], v[38:39], 0, v[48:49]
	v_pk_add_f32 v[26:27], v[26:27], v[40:41]
	global_store_dwordx4 v[44:45], v[30:33], off
	global_store_dwordx4 v[44:45], v[26:29], off offset:16
	v_mov_b32_e32 v36, v212
	v_mov_b32_e32 v37, v213
	v_mov_b32_e32 v38, v214
	v_mov_b32_e32 v39, v215
	v_mov_b32_e32 v40, v216
	v_mov_b32_e32 v41, v217
	v_mov_b32_e32 v42, v218
	v_mov_b32_e32 v43, v219
	v_pk_add_f32 v[20:21], v[20:21], v[38:39]
	v_pk_add_f32 v[24:25], v[24:25], v[42:43]
	v_pk_add_f32 v[22:23], v[22:23], v[40:41]
	v_pk_add_f32 v[18:19], v[18:19], v[36:37]
	global_store_dwordx4 v[44:45], v[22:25], off offset:512
	global_store_dwordx4 v[44:45], v[18:21], off offset:528
	v_mov_b32_e32 v37, v22
	v_mov_b32_e32 v22, v31
	v_mov_b32_e32 v36, v30
	v_pk_mul_f32 v[22:23], v[22:23], v[22:23]
	v_mov_b32_e32 v30, v32
	v_pk_fma_f32 v[22:23], v[36:37], v[36:37], v[22:23]
	v_mov_b32_e32 v31, v24
	v_pk_fma_f32 v[22:23], v[30:31], v[30:31], v[22:23]
	v_mov_b32_e32 v24, v33
	v_pk_fma_f32 v[22:23], v[24:25], v[24:25], v[22:23]
	v_mov_b32_e32 v24, v26
	v_mov_b32_e32 v25, v18
	v_pk_fma_f32 v[22:23], v[24:25], v[24:25], v[22:23]
	v_mov_b32_e32 v18, v27
	v_pk_fma_f32 v[18:19], v[18:19], v[18:19], v[22:23]
	v_mov_b32_e32 v22, v28
	v_mov_b32_e32 v23, v20
	v_pk_fma_f32 v[18:19], v[22:23], v[22:23], v[18:19]
	v_mov_b32_e32 v20, v29
	v_pk_fma_f32 v[18:19], v[20:21], v[20:21], v[18:19]
	s_nop 0
	v_add_f32_e32 v0, v18, v19

;     __device__ __forceinline__ void operator()(const f32x4 (&acc)[2][2][4][2], const Unit& u, int wr, int wc, int fr, int fq) const {
;     ...
;             for (int m = 0; m < 4; ++m) { const int row = row0 + ai * HALF + m * 16;
;                 const float* src = row_src(p, row); float* dst = row_dst(p, row); float ss = 0.f;
;                 if (dst) {
; #pragma unroll
;                     for (int bj = 0; bj < 2; ++bj) { const int col = col0 + bj * HALF;
;                         const f32x4 h0 = __builtin_nontemporal_load((const f32x4*)(src + col)), h1 = __builtin_nontemporal_load((const f32x4*)(src + col + 4));
;                         const f32x4 v0 = acc[ai][bj][m][0] + h0, v1 = acc[ai][bj][m][1] + h1;
;                         *(f32x4*)(dst + col) = v0; *(f32x4*)(dst + col + 4) = v1;
;                         ss += v0[0] * v0[0] + v0[1] * v0[1] + v0[2] * v0[2] + v0[3] * v0[3] + v1[0] * v1[0] + v1[1] * v1[1] + v1[2] * v1[2] + v1[3] * v1[3]; } }
;                 ss += __shfl_xor(ss, 16); ss += __shfl_xor(ss, 32);
;                 if (fq == 0) rss[(size_t)row * 32 + u.pn * 4 + wc] = ss; }
.LBB0_832:
	s_or_b64 exec, exec, s[0:1]
	v_cmp_ne_u64_e32 vcc, 0, v[22:23]
	v_mov_b32_e32 v0, 0
	s_and_saveexec_b64 s[0:1], vcc
	s_cbranch_execz .LBB0_834
	v_lshlrev_b64 v[32:33], 2, v[146:147]
	v_lshl_add_u64 v[34:35], v[20:21], 0, v[32:33]
	s_waitcnt vmcnt(0)
	v_mov_b32_e32 v24, v220
	v_mov_b32_e32 v25, v221
	v_mov_b32_e32 v26, v222
	v_mov_b32_e32 v27, v223
	v_mov_b32_e32 v28, v224
	v_mov_b32_e32 v29, v225
	v_mov_b32_e32 v30, v226
	v_mov_b32_e32 v31, v227
	v_pk_add_f32 v[12:13], v[12:13], v[26:27]
	v_pk_add_f32 v[16:17], v[16:17], v[30:31]
	v_pk_add_f32 v[14:15], v[14:15], v[28:29]
	v_lshl_add_u64 v[28:29], v[22:23], 0, v[32:33]
	v_pk_add_f32 v[10:11], v[10:11], v[24:25]
	global_store_dwordx4 v[28:29], v[14:17], off
	global_store_dwordx4 v[28:29], v[10:13], off offset:16
	v_mov_b32_e32 v20, v228
	v_mov_b32_e32 v21, v229
	v_mov_b32_e32 v22, v230
	v_mov_b32_e32 v23, v231
	v_mov_b32_e32 v24, v232
	v_mov_b32_e32 v25, v233
	v_mov_b32_e32 v26, v234
	v_mov_b32_e32 v27, v235
	v_pk_add_f32 v[4:5], v[4:5], v[22:23]
	v_pk_add_f32 v[8:9], v[8:9], v[26:27]
	v_pk_add_f32 v[6:7], v[6:7], v[24:25]
	v_pk_add_f32 v[2:3], v[2:3], v[20:21]
	global_store_dwordx4 v[28:29], v[6:9], off offset:512
	global_store_dwordx4 v[28:29], v[2:5], off offset:528
	v_mov_b32_e32 v21, v6
	v_mov_b32_e32 v6, v15
	v_mov_b32_e32 v20, v14
	v_pk_mul_f32 v[6:7], v[6:7], v[6:7]
	v_mov_b32_e32 v14, v16
	v_pk_fma_f32 v[6:7], v[20:21], v[20:21], v[6:7]
	v_mov_b32_e32 v15, v8
	v_pk_fma_f32 v[6:7], v[14:15], v[14:15], v[6:7]
	v_mov_b32_e32 v8, v17
	v_pk_fma_f32 v[6:7], v[8:9], v[8:9], v[6:7]
	v_mov_b32_e32 v8, v10
	v_mov_b32_e32 v9, v2
	v_pk_fma_f32 v[6:7], v[8:9], v[8:9], v[6:7]
	v_mov_b32_e32 v2, v11
	v_pk_fma_f32 v[2:3], v[2:3], v[2:3], v[6:7]
	v_mov_b32_e32 v6, v12
	v_mov_b32_e32 v7, v4
	v_pk_fma_f32 v[2:3], v[6:7], v[6:7], v[2:3]
	v_mov_b32_e32 v4, v13
	v_pk_fma_f32 v[2:3], v[4:5], v[4:5], v[2:3]
	s_nop 0
	v_add_f32_e32 v0, v2, v3

.LBB0_848:
	s_add_u32 s24, s36, 0xfff00080
	s_addc_u32 s25, s37, -1
	s_add_i32 s75, 0, 0x10000
	v_add_u32_e32 v152, s75, v159
	ds_read_b128 v[140:143], v152
	ds_read_b128 v[144:147], v152 offset:1024
	ds_read_b128 v[148:151], v152 offset:2048
	ds_read_b128 v[152:155], v152 offset:3072
	s_cmp_eq_u32 s74, 28
	s_cselect_b32 s39, s29, s25
	s_cselect_b32 s38, s70, s24
	s_cselect_b32 s25, s27, s73
	s_cselect_b32 s24, s71, s72
	v_lshl_add_u64 v[156:157], s[36:37], 0, v[136:137]
	s_add_i32 m0, s40, 0xc000
	ds_read_b128 v[162:165], v161
	ds_read_b128 v[166:169], v161 offset:1024
	ds_read_b128 v[180:183], v161 offset:2048
	ds_read_b128 v[184:187], v161 offset:3072
	ds_read_b128 v[188:191], v161 offset:4096
	ds_read_b128 v[204:207], v161 offset:5120
	ds_read_b128 v[208:211], v161 offset:6144
	ds_read_b128 v[212:215], v161 offset:7168
	global_load_lds_dwordx4 v[156:157], off
	v_lshl_add_u64 v[156:157], s[36:37], 0, v[138:139]
	s_add_i32 m0, s40, 0xe000
	s_nop 0
	global_load_lds_dwordx4 v[156:157], off
	s_waitcnt lgkmcnt(8)
	s_barrier
	s_waitcnt lgkmcnt(0)
	s_setprio 1
	s_waitcnt lgkmcnt(0)
	v_mfma_f32_16x16x32_bf16 v[126:129], v[140:143], v[162:165], v[126:129]
	v_mfma_f32_16x16x32_bf16 v[122:125], v[148:151], v[162:165], v[122:125]
	v_mfma_f32_16x16x32_bf16 v[110:113], v[140:143], v[180:183], v[110:113]
	v_mfma_f32_16x16x32_bf16 v[106:109], v[148:151], v[180:183], v[106:109]
	v_mfma_f32_16x16x32_bf16 v[94:97], v[140:143], v[188:191], v[94:97]
	v_mfma_f32_16x16x32_bf16 v[90:93], v[148:151], v[188:191], v[90:93]
	v_mfma_f32_16x16x32_bf16 v[78:81], v[140:143], v[208:211], v[78:81]
	v_mfma_f32_16x16x32_bf16 v[74:77], v[148:151], v[208:211], v[74:77]
	v_mfma_f32_16x16x32_bf16 v[126:129], v[144:147], v[166:169], v[126:129]
	v_mfma_f32_16x16x32_bf16 v[122:125], v[152:155], v[166:169], v[122:125]
	v_mfma_f32_16x16x32_bf16 v[110:113], v[144:147], v[184:187], v[110:113]
	v_mfma_f32_16x16x32_bf16 v[106:109], v[152:155], v[184:187], v[106:109]
	v_mfma_f32_16x16x32_bf16 v[94:97], v[144:147], v[204:207], v[94:97]
	v_mfma_f32_16x16x32_bf16 v[90:93], v[152:155], v[204:207], v[90:93]
	v_mfma_f32_16x16x32_bf16 v[78:81], v[144:147], v[212:215], v[78:81]
	v_mfma_f32_16x16x32_bf16 v[74:77], v[152:155], v[212:215], v[74:77]
	s_setprio 0
	s_barrier
	s_add_i32 s83, 0, 0x14000
	v_add_u32_e32 v156, s83, v159
	s_add_i32 s75, s75, s3
	ds_read_b128 v[216:219], v156
	ds_read_b128 v[220:223], v156 offset:1024
	ds_read_b128 v[224:227], v156 offset:2048
	ds_read_b128 v[228:231], v156 offset:3072
	v_lshl_add_u64 v[156:157], s[24:25], 0, v[0:1]
	s_mov_b32 m0, s75
	v_lshl_add_u64 v[170:171], s[24:25], 0, v[134:135]
	global_load_lds_dwordx4 v[156:157], off
	s_add_i32 m0, s75, 0x2000
	s_nop 0
	global_load_lds_dwordx4 v[170:171], off
	s_barrier
	s_waitcnt lgkmcnt(0)
	s_setprio 1
	s_waitcnt lgkmcnt(0)
	v_mfma_f32_16x16x32_bf16 v[118:121], v[216:219], v[162:165], v[118:121]
	v_mfma_f32_16x16x32_bf16 v[114:117], v[224:227], v[162:165], v[114:117]
	v_mfma_f32_16x16x32_bf16 v[102:105], v[216:219], v[180:183], v[102:105]
	v_mfma_f32_16x16x32_bf16 v[98:101], v[224:227], v[180:183], v[98:101]
	v_mfma_f32_16x16x32_bf16 v[86:89], v[216:219], v[188:191], v[86:89]
	v_mfma_f32_16x16x32_bf16 v[82:85], v[224:227], v[188:191], v[82:85]
	v_mfma_f32_16x16x32_bf16 v[70:73], v[216:219], v[208:211], v[70:73]
	v_mfma_f32_16x16x32_bf16 v[66:69], v[224:227], v[208:211], v[66:69]
	v_mfma_f32_16x16x32_bf16 v[118:121], v[220:223], v[166:169], v[118:121]
	v_mfma_f32_16x16x32_bf16 v[114:117], v[228:231], v[166:169], v[114:117]
	v_mfma_f32_16x16x32_bf16 v[102:105], v[220:223], v[184:187], v[102:105]
	v_mfma_f32_16x16x32_bf16 v[98:101], v[228:231], v[184:187], v[98:101]
	v_mfma_f32_16x16x32_bf16 v[86:89], v[220:223], v[204:207], v[86:89]
	v_mfma_f32_16x16x32_bf16 v[82:85], v[228:231], v[204:207], v[82:85]
	v_mfma_f32_16x16x32_bf16 v[70:73], v[220:223], v[212:215], v[70:73]
	v_mfma_f32_16x16x32_bf16 v[66:69], v[228:231], v[212:215], v[66:69]
	s_setprio 0
	s_mov_b32 m0, s40
	v_lshl_add_u64 v[232:233], s[38:39], 0, v[130:131]
	s_barrier
	ds_read_b128 v[162:165], v161 offset:16384
	ds_read_b128 v[166:169], v161 offset:17408
	ds_read_b128 v[180:183], v161 offset:18432
	ds_read_b128 v[184:187], v161 offset:19456
	ds_read_b128 v[188:191], v161 offset:20480
	ds_read_b128 v[204:207], v161 offset:21504
	ds_read_b128 v[208:211], v161 offset:22528
	ds_read_b128 v[212:215], v161 offset:23552
	global_load_lds_dwordx4 v[232:233], off
	v_lshl_add_u64 v[234:235], s[38:39], 0, v[132:133]
	s_mov_b32 m0, s41
	s_nop 0
	global_load_lds_dwordx4 v[234:235], off
	s_barrier
	s_waitcnt lgkmcnt(0)
	s_setprio 1
	s_waitcnt lgkmcnt(0)
	v_mfma_f32_16x16x32_bf16 v[62:65], v[140:143], v[162:165], v[62:65]
	v_mfma_f32_16x16x32_bf16 v[58:61], v[148:151], v[162:165], v[58:61]
	v_mfma_f32_16x16x32_bf16 v[46:49], v[140:143], v[180:183], v[46:49]
	v_mfma_f32_16x16x32_bf16 v[42:45], v[148:151], v[180:183], v[42:45]
	v_mfma_f32_16x16x32_bf16 v[30:33], v[140:143], v[188:191], v[30:33]
	v_mfma_f32_16x16x32_bf16 v[26:29], v[148:151], v[188:191], v[26:29]
	v_mfma_f32_16x16x32_bf16 v[14:17], v[140:143], v[208:211], v[14:17]
	v_mfma_f32_16x16x32_bf16 v[10:13], v[148:151], v[208:211], v[10:13]
	v_mfma_f32_16x16x32_bf16 v[62:65], v[144:147], v[166:169], v[62:65]
	v_mfma_f32_16x16x32_bf16 v[58:61], v[152:155], v[166:169], v[58:61]
	v_mfma_f32_16x16x32_bf16 v[46:49], v[144:147], v[184:187], v[46:49]
	v_mfma_f32_16x16x32_bf16 v[42:45], v[152:155], v[184:187], v[42:45]
	v_mfma_f32_16x16x32_bf16 v[30:33], v[144:147], v[204:207], v[30:33]
	v_mfma_f32_16x16x32_bf16 v[26:29], v[152:155], v[204:207], v[26:29]
	v_mfma_f32_16x16x32_bf16 v[14:17], v[144:147], v[212:215], v[14:17]
	v_mfma_f32_16x16x32_bf16 v[10:13], v[152:155], v[212:215], v[10:13]
	s_setprio 0
	s_barrier
	s_add_u32 s94, s24, 0x100000
	s_addc_u32 s95, s25, 0
	s_add_i32 s75, s83, s3
	v_lshl_add_u64 v[140:141], s[94:95], 0, v[0:1]
	s_mov_b32 m0, s75
	s_nop 0
	global_load_lds_dwordx4 v[140:141], off
	v_lshl_add_u64 v[140:141], s[94:95], 0, v[134:135]
	s_add_i32 m0, s75, 0x2000
	s_nop 0
	global_load_lds_dwordx4 v[140:141], off
	s_waitcnt vmcnt(6)
	s_barrier
	s_setprio 1
	v_mfma_f32_16x16x32_bf16 v[54:57], v[216:219], v[162:165], v[54:57]
	v_mfma_f32_16x16x32_bf16 v[50:53], v[224:227], v[162:165], v[50:53]
	v_mfma_f32_16x16x32_bf16 v[38:41], v[216:219], v[180:183], v[38:41]
	v_mfma_f32_16x16x32_bf16 v[34:37], v[224:227], v[180:183], v[34:37]
	v_mfma_f32_16x16x32_bf16 v[22:25], v[216:219], v[188:191], v[22:25]
	v_mfma_f32_16x16x32_bf16 v[18:21], v[224:227], v[188:191], v[18:21]
	v_mfma_f32_16x16x32_bf16 v[6:9], v[216:219], v[208:211], v[6:9]
	v_mfma_f32_16x16x32_bf16 v[2:5], v[224:227], v[208:211], v[2:5]
	v_mfma_f32_16x16x32_bf16 v[54:57], v[220:223], v[166:169], v[54:57]
	v_mfma_f32_16x16x32_bf16 v[50:53], v[228:231], v[166:169], v[50:53]
	v_mfma_f32_16x16x32_bf16 v[38:41], v[220:223], v[184:187], v[38:41]
	v_mfma_f32_16x16x32_bf16 v[34:37], v[228:231], v[184:187], v[34:37]
	v_mfma_f32_16x16x32_bf16 v[22:25], v[220:223], v[204:207], v[22:25]
	v_mfma_f32_16x16x32_bf16 v[18:21], v[228:231], v[204:207], v[18:21]
	v_mfma_f32_16x16x32_bf16 v[6:9], v[220:223], v[212:215], v[6:9]
	v_mfma_f32_16x16x32_bf16 v[2:5], v[228:231], v[212:215], v[2:5]
	s_setprio 0
	s_add_i32 s75, 0, 0x18000
	v_add_u32_e32 v152, s75, v159
	s_barrier
	ds_read_b128 v[140:143], v152
	ds_read_b128 v[144:147], v152 offset:1024
	ds_read_b128 v[148:151], v152 offset:2048
	ds_read_b128 v[152:155], v152 offset:3072
	s_add_u32 s38, s38, 0x100000
	s_addc_u32 s39, s39, 0
	s_mov_b32 m0, s46
	v_lshl_add_u64 v[216:217], s[38:39], 0, v[130:131]
	ds_read_b128 v[162:165], v161 offset:32768
	ds_read_b128 v[166:169], v161 offset:33792
	ds_read_b128 v[180:183], v161 offset:34816
	ds_read_b128 v[184:187], v161 offset:35840
	ds_read_b128 v[188:191], v161 offset:36864
	ds_read_b128 v[204:207], v161 offset:37888
	ds_read_b128 v[208:211], v161 offset:38912
	ds_read_b128 v[212:215], v161 offset:39936
	global_load_lds_dwordx4 v[216:217], off
	v_lshl_add_u64 v[216:217], s[38:39], 0, v[132:133]
	s_mov_b32 m0, s47
	s_nop 0
	global_load_lds_dwordx4 v[216:217], off
	s_waitcnt lgkmcnt(8)
	s_barrier
	s_waitcnt lgkmcnt(0)
	s_setprio 1
	s_waitcnt lgkmcnt(0)
	v_mfma_f32_16x16x32_bf16 v[126:129], v[140:143], v[162:165], v[126:129]
	v_mfma_f32_16x16x32_bf16 v[122:125], v[148:151], v[162:165], v[122:125]
	v_mfma_f32_16x16x32_bf16 v[110:113], v[140:143], v[180:183], v[110:113]
	v_mfma_f32_16x16x32_bf16 v[106:109], v[148:151], v[180:183], v[106:109]
	v_mfma_f32_16x16x32_bf16 v[94:97], v[140:143], v[188:191], v[94:97]
	v_mfma_f32_16x16x32_bf16 v[90:93], v[148:151], v[188:191], v[90:93]
	v_mfma_f32_16x16x32_bf16 v[78:81], v[140:143], v[208:211], v[78:81]
	v_mfma_f32_16x16x32_bf16 v[74:77], v[148:151], v[208:211], v[74:77]
	v_mfma_f32_16x16x32_bf16 v[126:129], v[144:147], v[166:169], v[126:129]
	v_mfma_f32_16x16x32_bf16 v[122:125], v[152:155], v[166:169], v[122:125]
	v_mfma_f32_16x16x32_bf16 v[110:113], v[144:147], v[184:187], v[110:113]
	v_mfma_f32_16x16x32_bf16 v[106:109], v[152:155], v[184:187], v[106:109]
	v_mfma_f32_16x16x32_bf16 v[94:97], v[144:147], v[204:207], v[94:97]
	v_mfma_f32_16x16x32_bf16 v[90:93], v[152:155], v[204:207], v[90:93]
	v_mfma_f32_16x16x32_bf16 v[78:81], v[144:147], v[212:215], v[78:81]
	v_mfma_f32_16x16x32_bf16 v[74:77], v[152:155], v[212:215], v[74:77]
	s_setprio 0
	s_barrier
	s_add_i32 s38, 0, 0x1c000
	s_add_i32 s39, s75, s3
	v_add_u32_e32 v203, s38, v159
	v_lshl_add_u64 v[156:157], v[156:157], 0, s[48:49]
	s_mov_b32 m0, s39
	ds_read_b128 v[216:219], v203
	ds_read_b128 v[220:223], v203 offset:1024
	ds_read_b128 v[224:227], v203 offset:2048
	ds_read_b128 v[228:231], v203 offset:3072
	global_load_lds_dwordx4 v[156:157], off
	v_lshl_add_u64 v[156:157], v[170:171], 0, s[48:49]
	s_add_i32 m0, s39, 0x2000
	s_nop 0
	global_load_lds_dwordx4 v[156:157], off
	s_barrier
	s_waitcnt lgkmcnt(0)
	s_setprio 1
	s_waitcnt lgkmcnt(0)
	v_mfma_f32_16x16x32_bf16 v[118:121], v[216:219], v[162:165], v[118:121]
	v_mfma_f32_16x16x32_bf16 v[114:117], v[224:227], v[162:165], v[114:117]
	v_mfma_f32_16x16x32_bf16 v[102:105], v[216:219], v[180:183], v[102:105]
	v_mfma_f32_16x16x32_bf16 v[98:101], v[224:227], v[180:183], v[98:101]
	v_mfma_f32_16x16x32_bf16 v[86:89], v[216:219], v[188:191], v[86:89]
	v_mfma_f32_16x16x32_bf16 v[82:85], v[224:227], v[188:191], v[82:85]
	v_mfma_f32_16x16x32_bf16 v[70:73], v[216:219], v[208:211], v[70:73]
	v_mfma_f32_16x16x32_bf16 v[66:69], v[224:227], v[208:211], v[66:69]
	v_mfma_f32_16x16x32_bf16 v[118:121], v[220:223], v[166:169], v[118:121]
	v_mfma_f32_16x16x32_bf16 v[114:117], v[228:231], v[166:169], v[114:117]
	v_mfma_f32_16x16x32_bf16 v[102:105], v[220:223], v[184:187], v[102:105]
	v_mfma_f32_16x16x32_bf16 v[98:101], v[228:231], v[184:187], v[98:101]
	v_mfma_f32_16x16x32_bf16 v[86:89], v[220:223], v[204:207], v[86:89]
	v_mfma_f32_16x16x32_bf16 v[82:85], v[228:231], v[204:207], v[82:85]
	v_mfma_f32_16x16x32_bf16 v[70:73], v[220:223], v[212:215], v[70:73]
	v_mfma_f32_16x16x32_bf16 v[66:69], v[228:231], v[212:215], v[66:69]
	s_setprio 0
	s_mov_b32 m0, s50
	v_lshl_add_u64 v[156:157], v[232:233], 0, s[48:49]
	s_barrier
	ds_read_b128 v[162:165], v161 offset:49152
	ds_read_b128 v[166:169], v161 offset:50176
	ds_read_b128 v[180:183], v161 offset:51200
	ds_read_b128 v[184:187], v161 offset:52224
	ds_read_b128 v[188:191], v161 offset:53248
	ds_read_b128 v[204:207], v161 offset:54272
	ds_read_b128 v[208:211], v161 offset:55296
	ds_read_b128 v[212:215], v161 offset:56320
	global_load_lds_dwordx4 v[156:157], off
	v_lshl_add_u64 v[156:157], v[234:235], 0, s[48:49]
	s_mov_b32 m0, s51
	s_nop 0
	global_load_lds_dwordx4 v[156:157], off
	s_barrier
; __device__ __forceinline__ float bflo(unsigned w) { return __uint_as_float(w << 16); }
; __device__ __forceinline__ float bfhi(unsigned w) { return __uint_as_float(w & 0xffff0000u); }
; template <class Epi>
; __device__ __forceinline__ void gemm_phase(LAS unsigned char* lds, const GemmD g, const Epi& E) {
;     ...
;         for (int t = 0; t < nt; t += 2) PG8_KITER(t);
;     __device__ __forceinline__ void operator()(const f32x4 (&acc)[2][2][4][2], const Unit& u, int wr, int wc, int fr, int fq) const {
;         const int row0 = u.pm * BM + wr * 64 + fr, col0 = u.pn * BM + wc * 32 + 8 * fq;
; #pragma unroll
;         for (int ai = 0; ai < 2; ++ai)
; #pragma unroll
;             for (int m = 0; m < 4; ++m) { const int row = row0 + ai * HALF + m * 16;
; #pragma unroll
;                 for (int bj = 0; bj < 2; ++bj) { const int col = col0 + bj * HALF;
;                     const u32x4 gp = *(const u32x4*)(proj + (size_t)row * NPROJ + C_GP + col);
;                     f32x4 f0 = (f32x4){bflo(gp.x), bfhi(gp.x), bflo(gp.y), bfhi(gp.y)}, f1 = (f32x4){bflo(gp.z), bfhi(gp.z), bflo(gp.w), bfhi(gp.w)};
;                     if (which == 0) { const u32x4 r = *(const u32x4*)(proj + (size_t)row * NPROJ + C_GS + col);
;                         f0 *= (f32x4){bflo(r.x), bfhi(r.x), bflo(r.y), bfhi(r.y)}; f1 *= (f32x4){bflo(r.z), bfhi(r.z), bflo(r.w), bfhi(r.w)}; }
;                     float* d = F + (size_t)(row - 8192) * DM + col;
;                     *(f32x4*)d = acc[ai][bj][m][0] * f0; *(f32x4*)(d + 4) = acc[ai][bj][m][1] * f1; } }
	s_waitcnt lgkmcnt(0)
	s_setprio 1
	s_waitcnt lgkmcnt(0)
	v_mfma_f32_16x16x32_bf16 v[62:65], v[140:143], v[162:165], v[62:65]
	v_mfma_f32_16x16x32_bf16 v[58:61], v[148:151], v[162:165], v[58:61]
	v_mfma_f32_16x16x32_bf16 v[46:49], v[140:143], v[180:183], v[46:49]
	v_mfma_f32_16x16x32_bf16 v[42:45], v[148:151], v[180:183], v[42:45]
	v_mfma_f32_16x16x32_bf16 v[30:33], v[140:143], v[188:191], v[30:33]
	v_mfma_f32_16x16x32_bf16 v[26:29], v[148:151], v[188:191], v[26:29]
	v_mfma_f32_16x16x32_bf16 v[14:17], v[140:143], v[208:211], v[14:17]
	v_mfma_f32_16x16x32_bf16 v[10:13], v[148:151], v[208:211], v[10:13]
	v_mfma_f32_16x16x32_bf16 v[62:65], v[144:147], v[166:169], v[62:65]
	v_mfma_f32_16x16x32_bf16 v[58:61], v[152:155], v[166:169], v[58:61]
	v_mfma_f32_16x16x32_bf16 v[46:49], v[144:147], v[184:187], v[46:49]
	v_mfma_f32_16x16x32_bf16 v[42:45], v[152:155], v[184:187], v[42:45]
	v_mfma_f32_16x16x32_bf16 v[30:33], v[144:147], v[204:207], v[30:33]
	v_mfma_f32_16x16x32_bf16 v[26:29], v[152:155], v[204:207], v[26:29]
	v_mfma_f32_16x16x32_bf16 v[14:17], v[144:147], v[212:215], v[14:17]
	v_mfma_f32_16x16x32_bf16 v[10:13], v[152:155], v[212:215], v[10:13]
	s_setprio 0
	s_barrier
	s_add_u32 s24, s24, 0x100080
	s_addc_u32 s25, s25, 0
	s_add_i32 s38, s38, s3
	v_lshl_add_u64 v[140:141], s[24:25], 0, v[0:1]
	s_mov_b32 m0, s38
	s_nop 0
	global_load_lds_dwordx4 v[140:141], off
	v_lshl_add_u64 v[140:141], s[24:25], 0, v[134:135]
	s_add_i32 m0, s38, 0x2000
	s_nop 0
	global_load_lds_dwordx4 v[140:141], off
	s_waitcnt vmcnt(6)
	s_barrier
	s_setprio 1
	v_mfma_f32_16x16x32_bf16 v[54:57], v[216:219], v[162:165], v[54:57]
	v_mfma_f32_16x16x32_bf16 v[50:53], v[224:227], v[162:165], v[50:53]
	v_mfma_f32_16x16x32_bf16 v[38:41], v[216:219], v[180:183], v[38:41]
	v_mfma_f32_16x16x32_bf16 v[34:37], v[224:227], v[180:183], v[34:37]
	v_mfma_f32_16x16x32_bf16 v[22:25], v[216:219], v[188:191], v[22:25]
	v_mfma_f32_16x16x32_bf16 v[18:21], v[224:227], v[188:191], v[18:21]
	v_mfma_f32_16x16x32_bf16 v[6:9], v[216:219], v[208:211], v[6:9]
	v_mfma_f32_16x16x32_bf16 v[2:5], v[224:227], v[208:211], v[2:5]
	v_mfma_f32_16x16x32_bf16 v[54:57], v[220:223], v[166:169], v[54:57]
	v_mfma_f32_16x16x32_bf16 v[50:53], v[228:231], v[166:169], v[50:53]
	v_mfma_f32_16x16x32_bf16 v[38:41], v[220:223], v[184:187], v[38:41]
	v_mfma_f32_16x16x32_bf16 v[34:37], v[228:231], v[184:187], v[34:37]
	v_mfma_f32_16x16x32_bf16 v[22:25], v[220:223], v[204:207], v[22:25]
	v_mfma_f32_16x16x32_bf16 v[18:21], v[228:231], v[204:207], v[18:21]
	v_mfma_f32_16x16x32_bf16 v[6:9], v[220:223], v[212:215], v[6:9]
	v_mfma_f32_16x16x32_bf16 v[2:5], v[228:231], v[212:215], v[2:5]
	s_setprio 0
	s_add_i32 s74, s74, 2
	s_add_u32 s36, s36, 0x100
	s_addc_u32 s37, s37, 0
	s_add_u32 s72, s72, 0x100
	s_addc_u32 s73, s73, 0
	s_cmp_gt_u32 s74, 29
	s_barrier
	s_cbranch_scc0 .LBB0_848
	v_lshl_add_u32 v142, s66, 8, v158
	v_mov_b64_e32 v[144:145], s[92:93]
	v_lshl_or_b32 v140, s57, 8, v160
	v_mad_i64_i32 v[144:145], s[24:25], v142, s91, v[144:145]
	v_lshl_add_u64 v[148:149], v[144:145], 0, s[76:77]
	v_ashrrev_i32_e32 v141, 31, v140
	v_lshl_add_u64 v[146:147], v[140:141], 1, v[148:149]
	v_mov_b32_e32 v240, v146
	v_mov_b32_e32 v241, v147
	s_mov_b32 s74, 0x0
	s_mov_b32 s75, 0
	v_lshl_add_u64 v[204:205], v[240:241], 0, s[74:75]
	global_load_dwordx4 v[204:207], v[204:205], off
	s_mov_b32 s74, 0xfffff000
	s_mov_b32 s75, -1
	v_lshl_add_u64 v[208:209], v[240:241], 0, s[74:75]
	global_load_dwordx4 v[208:211], v[208:209], off
	s_mov_b32 s74, 0x100
	s_mov_b32 s75, 0
	v_lshl_add_u64 v[212:213], v[240:241], 0, s[74:75]
	global_load_dwordx4 v[212:215], v[212:213], off
	s_mov_b32 s74, 0xfffff100
	s_mov_b32 s75, -1
	v_lshl_add_u64 v[216:217], v[240:241], 0, s[74:75]
	global_load_dwordx4 v[216:219], v[216:217], off
	s_mov_b32 s74, 0x6a000
	s_mov_b32 s75, 0
	v_lshl_add_u64 v[220:221], v[240:241], 0, s[74:75]
	global_load_dwordx4 v[220:223], v[220:221], off
	s_mov_b32 s74, 0x69000
	s_mov_b32 s75, 0
	v_lshl_add_u64 v[224:225], v[240:241], 0, s[74:75]
	global_load_dwordx4 v[224:227], v[224:225], off
	s_mov_b32 s74, 0x6a100
	s_mov_b32 s75, 0
	v_lshl_add_u64 v[228:229], v[240:241], 0, s[74:75]
	global_load_dwordx4 v[228:231], v[228:229], off
	s_mov_b32 s74, 0x69100
	s_mov_b32 s75, 0
	v_lshl_add_u64 v[232:233], v[240:241], 0, s[74:75]
	global_load_dwordx4 v[232:235], v[232:233], off
	s_mov_b32 s74, 0xd4000
	s_mov_b32 s75, 0
	v_lshl_add_u64 v[236:237], v[240:241], 0, s[74:75]
	global_load_dwordx4 v[236:239], v[236:237], off
	s_mov_b32 s74, 0xd3000
	s_mov_b32 s75, 0
	v_lshl_add_u64 v[180:181], v[240:241], 0, s[74:75]
	global_load_dwordx4 v[180:183], v[180:181], off
	s_mov_b32 s74, 0xd4100
	s_mov_b32 s75, 0
	v_lshl_add_u64 v[184:185], v[240:241], 0, s[74:75]
	global_load_dwordx4 v[184:187], v[184:185], off
	s_mov_b32 s74, 0xd3100
	s_mov_b32 s75, 0
	v_lshl_add_u64 v[188:189], v[240:241], 0, s[74:75]
	global_load_dwordx4 v[188:191], v[188:189], off
	s_mov_b32 s74, 0x13e000
	s_mov_b32 s75, 0
	v_lshl_add_u64 v[166:167], v[240:241], 0, s[74:75]
	global_load_dwordx4 v[166:169], v[166:167], off
	s_mov_b32 s74, 0x13d000
	s_mov_b32 s75, 0
	v_lshl_add_u64 v[246:247], v[240:241], 0, s[74:75]
	global_load_dwordx4 v[246:249], v[246:247], off
	v_cndmask_b32_e64 v143, 0, 1, s[62:63]
	v_cmp_ne_u32_e64 s[36:37], 1, v143
	s_andn2_b64 vcc, exec, s[62:63]
	s_waitcnt vmcnt(13)
	v_mov_b32_e32 v150, v204
	v_mov_b32_e32 v151, v205
	v_mov_b32_e32 v152, v206
	v_mov_b32_e32 v153, v207
	s_mov_b32 s74, 0x13e100
	s_mov_b32 s75, 0
	v_lshl_add_u64 v[204:205], v[240:241], 0, s[74:75]
	global_load_dwordx4 v[204:207], v[204:205], off
	v_lshlrev_b32_e32 v154, 16, v150
	v_and_b32_e32 v155, 0xffff0000, v150
	v_lshlrev_b32_e32 v156, 16, v151
	v_and_b32_e32 v157, 0xffff0000, v151
	v_lshlrev_b32_e32 v150, 16, v152
	v_and_b32_e32 v151, 0xffff0000, v152
	v_lshlrev_b32_e32 v152, 16, v153
	v_and_b32_e32 v153, 0xffff0000, v153
	s_cbranch_vccnz .LBB0_851
	v_lshl_add_u64 v[146:147], v[140:141], 1, v[144:145]
	v_add_co_u32_e32 v146, vcc, 0x4000, v146
	s_nop 1
	v_addc_co_u32_e32 v147, vcc, 0, v147, vcc
	s_waitcnt vmcnt(13)
	v_mov_b32_e32 v162, v208
	v_mov_b32_e32 v163, v209
	v_mov_b32_e32 v164, v210
	v_mov_b32_e32 v165, v211
	v_lshlrev_b32_e32 v146, 16, v162
	v_and_b32_e32 v147, 0xffff0000, v162
	v_lshlrev_b32_e32 v162, 16, v163
	v_and_b32_e32 v163, 0xffff0000, v163
	v_pk_mul_f32 v[156:157], v[156:157], v[162:163]
	v_pk_mul_f32 v[154:155], v[154:155], v[146:147]
	v_lshlrev_b32_e32 v146, 16, v164
	v_and_b32_e32 v147, 0xffff0000, v164
	v_lshlrev_b32_e32 v162, 16, v165
	v_and_b32_e32 v163, 0xffff0000, v165
	v_pk_mul_f32 v[152:153], v[152:153], v[162:163]
	v_pk_mul_f32 v[150:151], v[150:151], v[146:147]
; __device__ __forceinline__ float bflo(unsigned w) { return __uint_as_float(w << 16); }
; __device__ __forceinline__ float bfhi(unsigned w) { return __uint_as_float(w & 0xffff0000u); }
;     __device__ __forceinline__ void operator()(const f32x4 (&acc)[2][2][4][2], const Unit& u, int wr, int wc, int fr, int fq) const {
;     ...
;             for (int m = 0; m < 4; ++m) { const int row = row0 + ai * HALF + m * 16;
; #pragma unroll
;                 for (int bj = 0; bj < 2; ++bj) { const int col = col0 + bj * HALF;
;                     const u32x4 gp = *(const u32x4*)(proj + (size_t)row * NPROJ + C_GP + col);
;                     f32x4 f0 = (f32x4){bflo(gp.x), bfhi(gp.x), bflo(gp.y), bfhi(gp.y)}, f1 = (f32x4){bflo(gp.z), bfhi(gp.z), bflo(gp.w), bfhi(gp.w)};
;                     if (which == 0) { const u32x4 r = *(const u32x4*)(proj + (size_t)row * NPROJ + C_GS + col);
;                         f0 *= (f32x4){bflo(r.x), bfhi(r.x), bflo(r.y), bfhi(r.y)}; f1 *= (f32x4){bflo(r.z), bfhi(r.z), bflo(r.w), bfhi(r.w)}; }
;                     float* d = F + (size_t)(row - 8192) * DM + col;
;                     *(f32x4*)d = acc[ai][bj][m][0] * f0; *(f32x4*)(d + 4) = acc[ai][bj][m][1] * f1; } }
.LBB0_851:
	s_mov_b32 s74, 0x13d100
	s_mov_b32 s75, 0
	v_lshl_add_u64 v[208:209], v[240:241], 0, s[74:75]
	global_load_dwordx4 v[208:211], v[208:209], off
	v_ashrrev_i32_e32 v143, 31, v142
	v_lshlrev_b64 v[146:147], 13, v[142:143]
	v_lshl_add_u64 v[146:147], s[64:65], 0, v[146:147]
	s_brev_b32 s24, 63
	v_lshl_add_u64 v[162:163], v[140:141], 2, v[146:147]
	s_mov_b32 s25, -1
	v_lshl_add_u64 v[146:147], v[162:163], 0, s[24:25]
	s_brev_b32 s24, 63
	v_pk_mul_f32 v[124:125], v[124:125], v[152:153]
	v_pk_mul_f32 v[122:123], v[122:123], v[150:151]
	v_pk_mul_f32 v[126:127], v[126:127], v[154:155]
	v_add_co_u32_e32 v154, vcc, s24, v162
	global_store_dwordx4 v[146:147], v[122:125], off offset:16
	v_pk_mul_f32 v[128:129], v[128:129], v[156:157]
	v_addc_co_u32_e32 v155, vcc, -1, v163, vcc
	v_or_b32_e32 v122, 0x80, v140
	v_ashrrev_i32_e32 v123, 31, v122
	global_store_dwordx4 v[154:155], v[126:129], off
	v_lshl_add_u64 v[124:125], v[122:123], 1, v[148:149]
	s_and_b64 vcc, exec, s[36:37]
	s_waitcnt vmcnt(15)
	v_mov_b32_e32 v124, v212
	v_mov_b32_e32 v125, v213
	v_mov_b32_e32 v126, v214
	v_mov_b32_e32 v127, v215
	s_mov_b32 s74, 0x350000
	s_mov_b32 s75, 0
	v_lshl_add_u64 v[212:213], v[240:241], 0, s[74:75]
	global_load_dwordx4 v[212:215], v[212:213], off
	v_lshlrev_b32_e32 v128, 16, v124
	v_and_b32_e32 v129, 0xffff0000, v124
	v_lshlrev_b32_e32 v148, 16, v125
	v_and_b32_e32 v149, 0xffff0000, v125
	v_lshlrev_b32_e32 v124, 16, v126
	v_and_b32_e32 v125, 0xffff0000, v126
	v_lshlrev_b32_e32 v126, 16, v127
	v_and_b32_e32 v127, 0xffff0000, v127
	s_cbranch_vccnz .LBB0_853
	v_lshl_add_u64 v[144:145], v[122:123], 1, v[144:145]
	v_add_co_u32_e32 v144, vcc, 0x4000, v144
	s_nop 1
	v_addc_co_u32_e32 v145, vcc, 0, v145, vcc
	s_waitcnt vmcnt(15)
	v_mov_b32_e32 v150, v216
	v_mov_b32_e32 v151, v217
	v_mov_b32_e32 v152, v218
	v_mov_b32_e32 v153, v219
	v_lshlrev_b32_e32 v144, 16, v150
	v_and_b32_e32 v145, 0xffff0000, v150
	v_lshlrev_b32_e32 v150, 16, v151
	v_and_b32_e32 v151, 0xffff0000, v151
	v_pk_mul_f32 v[148:149], v[148:149], v[150:151]
	v_pk_mul_f32 v[128:129], v[128:129], v[144:145]
	v_lshlrev_b32_e32 v144, 16, v152
	v_and_b32_e32 v145, 0xffff0000, v152
	v_lshlrev_b32_e32 v150, 16, v153
	v_and_b32_e32 v151, 0xffff0000, v153
	v_pk_mul_f32 v[126:127], v[126:127], v[150:151]
	v_pk_mul_f32 v[124:125], v[124:125], v[144:145]
.LBB0_853:
	s_mov_b32 s74, 0x34f000
	s_mov_b32 s75, 0
	v_lshl_add_u64 v[216:217], v[240:241], 0, s[74:75]
	global_load_dwordx4 v[216:219], v[216:217], off
	v_pk_mul_f32 v[116:117], v[116:117], v[126:127]
	v_pk_mul_f32 v[114:115], v[114:115], v[124:125]
	global_store_dwordx4 v[146:147], v[114:117], off offset:528
	v_pk_mul_f32 v[120:121], v[120:121], v[148:149]
	v_pk_mul_f32 v[118:119], v[118:119], v[128:129]
	v_or_b32_e32 v116, 16, v142
	v_mov_b64_e32 v[114:115], s[92:93]
	v_mad_i64_i32 v[114:115], s[24:25], v116, s91, v[114:115]
	global_store_dwordx4 v[146:147], v[118:121], off offset:512
	s_and_b64 vcc, exec, s[36:37]
	s_nop 0
	v_lshl_add_u64 v[118:119], v[114:115], 0, s[76:77]
	v_lshl_add_u64 v[116:117], v[140:141], 1, v[118:119]
	s_waitcnt vmcnt(17)
	v_mov_b32_e32 v144, v220
	v_mov_b32_e32 v145, v221
	v_mov_b32_e32 v146, v222
	v_mov_b32_e32 v147, v223
	s_mov_b32 s74, 0x350100
	s_mov_b32 s75, 0
	v_lshl_add_u64 v[220:221], v[240:241], 0, s[74:75]
	global_load_dwordx4 v[220:223], v[220:221], off
	v_lshlrev_b32_e32 v126, 16, v144
	v_and_b32_e32 v127, 0xffff0000, v144
	v_lshlrev_b32_e32 v128, 16, v145
	v_and_b32_e32 v129, 0xffff0000, v145
	v_lshlrev_b32_e32 v120, 16, v146
	v_and_b32_e32 v121, 0xffff0000, v146
	v_lshlrev_b32_e32 v124, 16, v147
	v_and_b32_e32 v125, 0xffff0000, v147
	s_cbranch_vccnz .LBB0_855
	v_lshl_add_u64 v[116:117], v[140:141], 1, v[114:115]
	v_add_co_u32_e32 v116, vcc, 0x4000, v116
	s_nop 1
	v_addc_co_u32_e32 v117, vcc, 0, v117, vcc
	s_waitcnt vmcnt(17)
	v_mov_b32_e32 v144, v224
	v_mov_b32_e32 v145, v225
	v_mov_b32_e32 v146, v226
	v_mov_b32_e32 v147, v227
	v_lshlrev_b32_e32 v116, 16, v144
	v_and_b32_e32 v117, 0xffff0000, v144
	v_lshlrev_b32_e32 v144, 16, v145
	v_and_b32_e32 v145, 0xffff0000, v145
	v_pk_mul_f32 v[128:129], v[128:129], v[144:145]
	v_pk_mul_f32 v[126:127], v[126:127], v[116:117]
	v_lshlrev_b32_e32 v116, 16, v146
	v_and_b32_e32 v117, 0xffff0000, v146
	v_lshlrev_b32_e32 v144, 16, v147
	v_and_b32_e32 v145, 0xffff0000, v147
	v_pk_mul_f32 v[124:125], v[124:125], v[144:145]
	v_pk_mul_f32 v[120:121], v[120:121], v[116:117]
.LBB0_855:
	s_mov_b32 s74, 0x34f100
	s_mov_b32 s75, 0
	v_lshl_add_u64 v[224:225], v[240:241], 0, s[74:75]
	global_load_dwordx4 v[224:227], v[224:225], off
	v_lshlrev_b64 v[116:117], 13, v[142:143]
	v_lshl_add_u64 v[116:117], s[64:65], 0, v[116:117]
	v_lshl_add_u64 v[144:145], v[140:141], 2, v[116:117]
	s_mov_b32 s24, 0xfc020000
	s_mov_b32 s25, -1
	v_pk_mul_f32 v[110:111], v[110:111], v[126:127]
	v_add_co_u32_e32 v126, vcc, 0xfc020000, v144
	v_lshl_add_u64 v[116:117], v[144:145], 0, s[24:25]
	v_pk_mul_f32 v[112:113], v[112:113], v[128:129]
	v_addc_co_u32_e32 v127, vcc, -1, v145, vcc
	v_pk_mul_f32 v[108:109], v[108:109], v[124:125]
	v_pk_mul_f32 v[106:107], v[106:107], v[120:121]
	global_store_dwordx4 v[126:127], v[110:113], off
	global_store_dwordx4 v[116:117], v[106:109], off offset:16
	s_and_b64 vcc, exec, s[36:37]
	s_nop 0
	v_lshl_add_u64 v[106:107], v[122:123], 1, v[118:119]
	s_waitcnt vmcnt(19)
	v_mov_b32_e32 v106, v228
	v_mov_b32_e32 v107, v229
	v_mov_b32_e32 v108, v230
	v_mov_b32_e32 v109, v231
	s_mov_b32 s74, 0x3ba000
	s_mov_b32 s75, 0
	v_lshl_add_u64 v[228:229], v[240:241], 0, s[74:75]
	global_load_dwordx4 v[228:231], v[228:229], off
	v_lshlrev_b32_e32 v110, 16, v106
	v_and_b32_e32 v111, 0xffff0000, v106
	v_lshlrev_b32_e32 v112, 16, v107
	v_and_b32_e32 v113, 0xffff0000, v107
	v_lshlrev_b32_e32 v106, 16, v108
	v_and_b32_e32 v107, 0xffff0000, v108
	v_lshlrev_b32_e32 v108, 16, v109
	v_and_b32_e32 v109, 0xffff0000, v109
	s_cbranch_vccnz .LBB0_857
	v_lshl_add_u64 v[114:115], v[122:123], 1, v[114:115]
	v_add_co_u32_e32 v114, vcc, 0x4000, v114
	s_nop 1
	v_addc_co_u32_e32 v115, vcc, 0, v115, vcc
	s_waitcnt vmcnt(19)
	v_mov_b32_e32 v118, v232
	v_mov_b32_e32 v119, v233
	v_mov_b32_e32 v120, v234
	v_mov_b32_e32 v121, v235
	v_lshlrev_b32_e32 v114, 16, v118
	v_and_b32_e32 v115, 0xffff0000, v118
	v_lshlrev_b32_e32 v118, 16, v119
	v_and_b32_e32 v119, 0xffff0000, v119
	v_pk_mul_f32 v[112:113], v[112:113], v[118:119]
	v_pk_mul_f32 v[110:111], v[110:111], v[114:115]
	v_lshlrev_b32_e32 v114, 16, v120
	v_and_b32_e32 v115, 0xffff0000, v120
	v_lshlrev_b32_e32 v118, 16, v121
	v_and_b32_e32 v119, 0xffff0000, v121
	v_pk_mul_f32 v[108:109], v[108:109], v[118:119]
	v_pk_mul_f32 v[106:107], v[106:107], v[114:115]
; __device__ __forceinline__ float bflo(unsigned w) { return __uint_as_float(w << 16); }
; __device__ __forceinline__ float bfhi(unsigned w) { return __uint_as_float(w & 0xffff0000u); }
;     __device__ __forceinline__ void operator()(const f32x4 (&acc)[2][2][4][2], const Unit& u, int wr, int wc, int fr, int fq) const {
;     ...
;             for (int m = 0; m < 4; ++m) { const int row = row0 + ai * HALF + m * 16;
; #pragma unroll
;                 for (int bj = 0; bj < 2; ++bj) { const int col = col0 + bj * HALF;
;                     const u32x4 gp = *(const u32x4*)(proj + (size_t)row * NPROJ + C_GP + col);
;                     f32x4 f0 = (f32x4){bflo(gp.x), bfhi(gp.x), bflo(gp.y), bfhi(gp.y)}, f1 = (f32x4){bflo(gp.z), bfhi(gp.z), bflo(gp.w), bfhi(gp.w)};
;                     if (which == 0) { const u32x4 r = *(const u32x4*)(proj + (size_t)row * NPROJ + C_GS + col);
;                         f0 *= (f32x4){bflo(r.x), bfhi(r.x), bflo(r.y), bfhi(r.y)}; f1 *= (f32x4){bflo(r.z), bfhi(r.z), bflo(r.w), bfhi(r.w)}; }
;                     float* d = F + (size_t)(row - 8192) * DM + col;
;                     *(f32x4*)d = acc[ai][bj][m][0] * f0; *(f32x4*)(d + 4) = acc[ai][bj][m][1] * f1; } }
.LBB0_857:
	s_mov_b32 s74, 0x3b9000
	s_mov_b32 s75, 0
	v_lshl_add_u64 v[232:233], v[240:241], 0, s[74:75]
	global_load_dwordx4 v[232:235], v[232:233], off
	v_pk_mul_f32 v[100:101], v[100:101], v[108:109]
	v_pk_mul_f32 v[98:99], v[98:99], v[106:107]
	global_store_dwordx4 v[116:117], v[98:101], off offset:528
	v_pk_mul_f32 v[104:105], v[104:105], v[112:113]
	v_pk_mul_f32 v[102:103], v[102:103], v[110:111]
	v_or_b32_e32 v100, 32, v142
	v_mov_b64_e32 v[98:99], s[92:93]
	v_mad_i64_i32 v[98:99], s[24:25], v100, s91, v[98:99]
	global_store_dwordx4 v[116:117], v[102:105], off offset:512
	s_and_b64 vcc, exec, s[36:37]
	s_nop 0
	v_lshl_add_u64 v[102:103], v[98:99], 0, s[76:77]
	v_lshl_add_u64 v[100:101], v[140:141], 1, v[102:103]
	s_waitcnt vmcnt(21)
	v_mov_b32_e32 v104, v236
	v_mov_b32_e32 v105, v237
	v_mov_b32_e32 v106, v238
	v_mov_b32_e32 v107, v239
	s_mov_b32 s74, 0x3ba100
	s_mov_b32 s75, 0
	v_lshl_add_u64 v[236:237], v[240:241], 0, s[74:75]
	global_load_dwordx4 v[236:239], v[236:237], off
	v_lshlrev_b32_e32 v108, 16, v104
	v_and_b32_e32 v109, 0xffff0000, v104
	v_lshlrev_b32_e32 v110, 16, v105
	v_and_b32_e32 v111, 0xffff0000, v105
	v_lshlrev_b32_e32 v104, 16, v106
	v_and_b32_e32 v105, 0xffff0000, v106
	v_lshlrev_b32_e32 v106, 16, v107
	v_and_b32_e32 v107, 0xffff0000, v107
	s_cbranch_vccnz .LBB0_859
	v_lshl_add_u64 v[100:101], v[140:141], 1, v[98:99]
	v_add_co_u32_e32 v100, vcc, 0x4000, v100
	s_nop 1
	v_addc_co_u32_e32 v101, vcc, 0, v101, vcc
	s_waitcnt vmcnt(21)
	v_mov_b32_e32 v112, v180
	v_mov_b32_e32 v113, v181
	v_mov_b32_e32 v114, v182
	v_mov_b32_e32 v115, v183
	v_lshlrev_b32_e32 v100, 16, v112
	v_and_b32_e32 v101, 0xffff0000, v112
	v_lshlrev_b32_e32 v112, 16, v113
	v_and_b32_e32 v113, 0xffff0000, v113
	v_pk_mul_f32 v[110:111], v[110:111], v[112:113]
	v_pk_mul_f32 v[108:109], v[108:109], v[100:101]
	v_lshlrev_b32_e32 v100, 16, v114
	v_and_b32_e32 v101, 0xffff0000, v114
	v_lshlrev_b32_e32 v112, 16, v115
	v_and_b32_e32 v113, 0xffff0000, v115
	v_pk_mul_f32 v[106:107], v[106:107], v[112:113]
	v_pk_mul_f32 v[104:105], v[104:105], v[100:101]
.LBB0_859:
	s_mov_b32 s74, 0x3b9100
	s_mov_b32 s75, 0
	v_lshl_add_u64 v[180:181], v[240:241], 0, s[74:75]
	global_load_dwordx4 v[180:183], v[180:181], off
	v_lshlrev_b64 v[100:101], 13, v[142:143]
	v_lshl_add_u64 v[100:101], s[64:65], 0, v[100:101]
	v_lshl_add_u64 v[112:113], v[140:141], 2, v[100:101]
	s_mov_b32 s24, 0xfc040000
	s_mov_b32 s25, -1
	v_pk_mul_f32 v[94:95], v[94:95], v[108:109]
	v_add_co_u32_e32 v108, vcc, 0xfc040000, v112
	v_lshl_add_u64 v[100:101], v[112:113], 0, s[24:25]
	v_pk_mul_f32 v[96:97], v[96:97], v[110:111]
	v_addc_co_u32_e32 v109, vcc, -1, v113, vcc
	v_pk_mul_f32 v[92:93], v[92:93], v[106:107]
	v_pk_mul_f32 v[90:91], v[90:91], v[104:105]
	global_store_dwordx4 v[108:109], v[94:97], off
	global_store_dwordx4 v[100:101], v[90:93], off offset:16
	s_and_b64 vcc, exec, s[36:37]
	s_nop 0
	v_lshl_add_u64 v[90:91], v[122:123], 1, v[102:103]
	s_waitcnt vmcnt(23)
	v_mov_b32_e32 v90, v184
	v_mov_b32_e32 v91, v185
	v_mov_b32_e32 v92, v186
	v_mov_b32_e32 v93, v187
	s_mov_b32 s74, 0x424000
	s_mov_b32 s75, 0
	v_lshl_add_u64 v[184:185], v[240:241], 0, s[74:75]
	global_load_dwordx4 v[184:187], v[184:185], off
	v_lshlrev_b32_e32 v94, 16, v90
	v_and_b32_e32 v95, 0xffff0000, v90
	v_lshlrev_b32_e32 v96, 16, v91
	v_and_b32_e32 v97, 0xffff0000, v91
	v_lshlrev_b32_e32 v90, 16, v92
	v_and_b32_e32 v91, 0xffff0000, v92
	v_lshlrev_b32_e32 v92, 16, v93
	v_and_b32_e32 v93, 0xffff0000, v93
	s_cbranch_vccnz .LBB0_861
	v_lshl_add_u64 v[98:99], v[122:123], 1, v[98:99]
	v_add_co_u32_e32 v98, vcc, 0x4000, v98
	s_nop 1
	v_addc_co_u32_e32 v99, vcc, 0, v99, vcc
	s_waitcnt vmcnt(23)
	v_mov_b32_e32 v102, v188
	v_mov_b32_e32 v103, v189
	v_mov_b32_e32 v104, v190
	v_mov_b32_e32 v105, v191
	v_lshlrev_b32_e32 v98, 16, v102
	v_and_b32_e32 v99, 0xffff0000, v102
	v_lshlrev_b32_e32 v102, 16, v103
	v_and_b32_e32 v103, 0xffff0000, v103
	v_pk_mul_f32 v[96:97], v[96:97], v[102:103]
	v_pk_mul_f32 v[94:95], v[94:95], v[98:99]
	v_lshlrev_b32_e32 v98, 16, v104
	v_and_b32_e32 v99, 0xffff0000, v104
	v_lshlrev_b32_e32 v102, 16, v105
	v_and_b32_e32 v103, 0xffff0000, v105
	v_pk_mul_f32 v[92:93], v[92:93], v[102:103]
	v_pk_mul_f32 v[90:91], v[90:91], v[98:99]
.LBB0_861:
	s_mov_b32 s74, 0x423000
	s_mov_b32 s75, 0
	v_lshl_add_u64 v[188:189], v[240:241], 0, s[74:75]
	global_load_dwordx4 v[188:191], v[188:189], off
	v_pk_mul_f32 v[84:85], v[84:85], v[92:93]
	v_pk_mul_f32 v[82:83], v[82:83], v[90:91]
	global_store_dwordx4 v[100:101], v[82:85], off offset:528
	v_pk_mul_f32 v[88:89], v[88:89], v[96:97]
	v_pk_mul_f32 v[86:87], v[86:87], v[94:95]
	v_or_b32_e32 v84, 48, v142
	v_mov_b64_e32 v[82:83], s[92:93]
	v_mad_i64_i32 v[82:83], s[24:25], v84, s91, v[82:83]
	global_store_dwordx4 v[100:101], v[86:89], off offset:512
	s_and_b64 vcc, exec, s[36:37]
	s_nop 0
	v_lshl_add_u64 v[86:87], v[82:83], 0, s[76:77]
	v_lshl_add_u64 v[84:85], v[140:141], 1, v[86:87]
	s_waitcnt vmcnt(25)
	v_mov_b32_e32 v88, v166
	v_mov_b32_e32 v89, v167
	v_mov_b32_e32 v90, v168
	v_mov_b32_e32 v91, v169
	s_mov_b32 s74, 0x424100
	s_mov_b32 s75, 0
	v_lshl_add_u64 v[166:167], v[240:241], 0, s[74:75]
	global_load_dwordx4 v[166:169], v[166:167], off
	v_lshlrev_b32_e32 v92, 16, v88
	v_and_b32_e32 v93, 0xffff0000, v88
	v_lshlrev_b32_e32 v94, 16, v89
	v_and_b32_e32 v95, 0xffff0000, v89
	v_lshlrev_b32_e32 v88, 16, v90
	v_and_b32_e32 v89, 0xffff0000, v90
	v_lshlrev_b32_e32 v90, 16, v91
	v_and_b32_e32 v91, 0xffff0000, v91
	s_cbranch_vccnz .LBB0_863
	v_lshl_add_u64 v[84:85], v[140:141], 1, v[82:83]
	v_add_co_u32_e32 v84, vcc, 0x4000, v84
	s_nop 1
	v_addc_co_u32_e32 v85, vcc, 0, v85, vcc
	s_waitcnt vmcnt(25)
	v_mov_b32_e32 v96, v246
	v_mov_b32_e32 v97, v247
	v_mov_b32_e32 v98, v248
	v_mov_b32_e32 v99, v249
	v_lshlrev_b32_e32 v84, 16, v96
	v_and_b32_e32 v85, 0xffff0000, v96
	v_lshlrev_b32_e32 v96, 16, v97
	v_and_b32_e32 v97, 0xffff0000, v97
	v_pk_mul_f32 v[94:95], v[94:95], v[96:97]
	v_pk_mul_f32 v[92:93], v[92:93], v[84:85]
	v_lshlrev_b32_e32 v84, 16, v98
	v_and_b32_e32 v85, 0xffff0000, v98
	v_lshlrev_b32_e32 v96, 16, v99
	v_and_b32_e32 v97, 0xffff0000, v99
	v_pk_mul_f32 v[90:91], v[90:91], v[96:97]
	v_pk_mul_f32 v[88:89], v[88:89], v[84:85]
; __device__ __forceinline__ float bflo(unsigned w) { return __uint_as_float(w << 16); }
; __device__ __forceinline__ float bfhi(unsigned w) { return __uint_as_float(w & 0xffff0000u); }
;     __device__ __forceinline__ void operator()(const f32x4 (&acc)[2][2][4][2], const Unit& u, int wr, int wc, int fr, int fq) const {
;         const int row0 = u.pm * BM + wr * 64 + fr, col0 = u.pn * BM + wc * 32 + 8 * fq;
; #pragma unroll
;         for (int ai = 0; ai < 2; ++ai)
; #pragma unroll
;             for (int m = 0; m < 4; ++m) { const int row = row0 + ai * HALF + m * 16;
; #pragma unroll
;                 for (int bj = 0; bj < 2; ++bj) { const int col = col0 + bj * HALF;
;                     const u32x4 gp = *(const u32x4*)(proj + (size_t)row * NPROJ + C_GP + col);
;                     f32x4 f0 = (f32x4){bflo(gp.x), bfhi(gp.x), bflo(gp.y), bfhi(gp.y)}, f1 = (f32x4){bflo(gp.z), bfhi(gp.z), bflo(gp.w), bfhi(gp.w)};
;                     if (which == 0) { const u32x4 r = *(const u32x4*)(proj + (size_t)row * NPROJ + C_GS + col);
;                         f0 *= (f32x4){bflo(r.x), bfhi(r.x), bflo(r.y), bfhi(r.y)}; f1 *= (f32x4){bflo(r.z), bfhi(r.z), bflo(r.w), bfhi(r.w)}; }
;                     float* d = F + (size_t)(row - 8192) * DM + col;
;                     *(f32x4*)d = acc[ai][bj][m][0] * f0; *(f32x4*)(d + 4) = acc[ai][bj][m][1] * f1; } }
;     }
.LBB0_863:
	s_mov_b32 s74, 0x423100
	s_mov_b32 s75, 0
	v_lshl_add_u64 v[246:247], v[240:241], 0, s[74:75]
	global_load_dwordx4 v[246:249], v[246:247], off
	v_lshlrev_b64 v[84:85], 13, v[142:143]
	v_lshl_add_u64 v[84:85], s[64:65], 0, v[84:85]
	v_lshl_add_u64 v[96:97], v[140:141], 2, v[84:85]
	s_mov_b32 s24, 0xfc060000
	s_mov_b32 s25, -1
	v_pk_mul_f32 v[78:79], v[78:79], v[92:93]
	v_add_co_u32_e32 v92, vcc, 0xfc060000, v96
	v_lshl_add_u64 v[84:85], v[96:97], 0, s[24:25]
	v_pk_mul_f32 v[80:81], v[80:81], v[94:95]
	v_addc_co_u32_e32 v93, vcc, -1, v97, vcc
	v_pk_mul_f32 v[76:77], v[76:77], v[90:91]
	v_pk_mul_f32 v[74:75], v[74:75], v[88:89]
	global_store_dwordx4 v[92:93], v[78:81], off
	global_store_dwordx4 v[84:85], v[74:77], off offset:16
	s_and_b64 vcc, exec, s[36:37]
	s_nop 0
	v_lshl_add_u64 v[74:75], v[122:123], 1, v[86:87]
	s_waitcnt vmcnt(27)
	v_mov_b32_e32 v74, v204
	v_mov_b32_e32 v75, v205
	v_mov_b32_e32 v76, v206
	v_mov_b32_e32 v77, v207
	s_mov_b32 s74, 0x48e000
	s_mov_b32 s75, 0
	v_lshl_add_u64 v[204:205], v[240:241], 0, s[74:75]
	global_load_dwordx4 v[204:207], v[204:205], off
	v_lshlrev_b32_e32 v78, 16, v74
	v_and_b32_e32 v79, 0xffff0000, v74
	v_lshlrev_b32_e32 v80, 16, v75
	v_and_b32_e32 v81, 0xffff0000, v75
	v_lshlrev_b32_e32 v74, 16, v76
	v_and_b32_e32 v75, 0xffff0000, v76
	v_lshlrev_b32_e32 v76, 16, v77
	v_and_b32_e32 v77, 0xffff0000, v77
	s_cbranch_vccnz .LBB0_865
	v_lshl_add_u64 v[82:83], v[122:123], 1, v[82:83]
	v_add_co_u32_e32 v82, vcc, 0x4000, v82
	s_nop 1
	v_addc_co_u32_e32 v83, vcc, 0, v83, vcc
	s_waitcnt vmcnt(27)
	v_mov_b32_e32 v86, v208
	v_mov_b32_e32 v87, v209
	v_mov_b32_e32 v88, v210
	v_mov_b32_e32 v89, v211
	v_lshlrev_b32_e32 v82, 16, v86
	v_and_b32_e32 v83, 0xffff0000, v86
	v_lshlrev_b32_e32 v86, 16, v87
	v_and_b32_e32 v87, 0xffff0000, v87
	v_pk_mul_f32 v[80:81], v[80:81], v[86:87]
	v_pk_mul_f32 v[78:79], v[78:79], v[82:83]
	v_lshlrev_b32_e32 v82, 16, v88
	v_and_b32_e32 v83, 0xffff0000, v88
	v_lshlrev_b32_e32 v86, 16, v89
	v_and_b32_e32 v87, 0xffff0000, v89
	v_pk_mul_f32 v[76:77], v[76:77], v[86:87]
	v_pk_mul_f32 v[74:75], v[74:75], v[82:83]
.LBB0_865:
	s_mov_b32 s74, 0x48d000
	s_mov_b32 s75, 0
	v_lshl_add_u64 v[208:209], v[240:241], 0, s[74:75]
	global_load_dwordx4 v[208:211], v[208:209], off
	v_pk_mul_f32 v[68:69], v[68:69], v[76:77]
	v_pk_mul_f32 v[66:67], v[66:67], v[74:75]
	global_store_dwordx4 v[84:85], v[66:69], off offset:528
	v_pk_mul_f32 v[72:73], v[72:73], v[80:81]
	v_pk_mul_f32 v[70:71], v[70:71], v[78:79]
	v_add_u32_e32 v68, 0x80, v142
	v_mov_b64_e32 v[66:67], s[92:93]
	v_mad_i64_i32 v[66:67], s[24:25], v68, s91, v[66:67]
	global_store_dwordx4 v[84:85], v[70:73], off offset:512
	s_and_b64 vcc, exec, s[36:37]
	s_nop 0
	v_lshl_add_u64 v[70:71], v[66:67], 0, s[76:77]
	v_lshl_add_u64 v[68:69], v[140:141], 1, v[70:71]
	s_waitcnt vmcnt(27)
	v_mov_b32_e32 v72, v212
	v_mov_b32_e32 v73, v213
	v_mov_b32_e32 v74, v214
	v_mov_b32_e32 v75, v215
	s_mov_b32 s74, 0x48e100
	s_mov_b32 s75, 0
	v_lshl_add_u64 v[212:213], v[240:241], 0, s[74:75]
	global_load_dwordx4 v[212:215], v[212:213], off
	v_lshlrev_b32_e32 v76, 16, v72
	v_and_b32_e32 v77, 0xffff0000, v72
	v_lshlrev_b32_e32 v78, 16, v73
	v_and_b32_e32 v79, 0xffff0000, v73
	v_lshlrev_b32_e32 v72, 16, v74
	v_and_b32_e32 v73, 0xffff0000, v74
	v_lshlrev_b32_e32 v74, 16, v75
	v_and_b32_e32 v75, 0xffff0000, v75
	s_cbranch_vccnz .LBB0_867
	v_lshl_add_u64 v[68:69], v[140:141], 1, v[66:67]
	v_add_co_u32_e32 v68, vcc, 0x4000, v68
	s_nop 1
	v_addc_co_u32_e32 v69, vcc, 0, v69, vcc
	s_waitcnt vmcnt(27)
	v_mov_b32_e32 v80, v216
	v_mov_b32_e32 v81, v217
	v_mov_b32_e32 v82, v218
	v_mov_b32_e32 v83, v219
	v_lshlrev_b32_e32 v68, 16, v80
	v_and_b32_e32 v69, 0xffff0000, v80
	v_lshlrev_b32_e32 v80, 16, v81
	v_and_b32_e32 v81, 0xffff0000, v81
	v_pk_mul_f32 v[78:79], v[78:79], v[80:81]
	v_pk_mul_f32 v[76:77], v[76:77], v[68:69]
	v_lshlrev_b32_e32 v68, 16, v82
	v_and_b32_e32 v69, 0xffff0000, v82
	v_lshlrev_b32_e32 v80, 16, v83
	v_and_b32_e32 v81, 0xffff0000, v83
	v_pk_mul_f32 v[74:75], v[74:75], v[80:81]
	v_pk_mul_f32 v[72:73], v[72:73], v[68:69]
.LBB0_867:
	s_mov_b32 s74, 0x48d100
	s_mov_b32 s75, 0
	v_lshl_add_u64 v[216:217], v[240:241], 0, s[74:75]
	global_load_dwordx4 v[216:219], v[216:217], off
	v_lshlrev_b64 v[68:69], 13, v[142:143]
	v_lshl_add_u64 v[68:69], s[64:65], 0, v[68:69]
	v_lshl_add_u64 v[80:81], v[140:141], 2, v[68:69]
	s_mov_b32 s24, 0xfc100000
	s_mov_b32 s25, -1
	v_pk_mul_f32 v[62:63], v[62:63], v[76:77]
	v_add_co_u32_e32 v76, vcc, 0xfc100000, v80
	v_lshl_add_u64 v[68:69], v[80:81], 0, s[24:25]
	v_pk_mul_f32 v[64:65], v[64:65], v[78:79]
	v_addc_co_u32_e32 v77, vcc, -1, v81, vcc
	v_pk_mul_f32 v[60:61], v[60:61], v[74:75]
	v_pk_mul_f32 v[58:59], v[58:59], v[72:73]
	global_store_dwordx4 v[76:77], v[62:65], off
	global_store_dwordx4 v[68:69], v[58:61], off offset:16
	s_and_b64 vcc, exec, s[36:37]
	s_nop 0
	v_lshl_add_u64 v[58:59], v[122:123], 1, v[70:71]
	s_waitcnt vmcnt(27)
	v_mov_b32_e32 v58, v220
	v_mov_b32_e32 v59, v221
	v_mov_b32_e32 v60, v222
	v_mov_b32_e32 v61, v223
	v_lshlrev_b32_e32 v62, 16, v58
	v_and_b32_e32 v63, 0xffff0000, v58
	v_lshlrev_b32_e32 v64, 16, v59
	v_and_b32_e32 v65, 0xffff0000, v59
	v_lshlrev_b32_e32 v58, 16, v60
	v_and_b32_e32 v59, 0xffff0000, v60
	v_lshlrev_b32_e32 v60, 16, v61
	v_and_b32_e32 v61, 0xffff0000, v61
	s_cbranch_vccnz .LBB0_869
	v_lshl_add_u64 v[66:67], v[122:123], 1, v[66:67]
	v_add_co_u32_e32 v66, vcc, 0x4000, v66
	s_nop 1
	v_addc_co_u32_e32 v67, vcc, 0, v67, vcc
	s_waitcnt vmcnt(26)
	v_mov_b32_e32 v70, v224
	v_mov_b32_e32 v71, v225
	v_mov_b32_e32 v72, v226
	v_mov_b32_e32 v73, v227
	v_lshlrev_b32_e32 v66, 16, v70
	v_and_b32_e32 v67, 0xffff0000, v70
	v_lshlrev_b32_e32 v70, 16, v71
	v_and_b32_e32 v71, 0xffff0000, v71
	v_pk_mul_f32 v[64:65], v[64:65], v[70:71]
	v_pk_mul_f32 v[62:63], v[62:63], v[66:67]
	v_lshlrev_b32_e32 v66, 16, v72
	v_and_b32_e32 v67, 0xffff0000, v72
	v_lshlrev_b32_e32 v70, 16, v73
	v_and_b32_e32 v71, 0xffff0000, v73
	v_pk_mul_f32 v[60:61], v[60:61], v[70:71]
	v_pk_mul_f32 v[58:59], v[58:59], v[66:67]
; __device__ __forceinline__ float bflo(unsigned w) { return __uint_as_float(w << 16); }
; __device__ __forceinline__ float bfhi(unsigned w) { return __uint_as_float(w & 0xffff0000u); }
;     __device__ __forceinline__ void operator()(const f32x4 (&acc)[2][2][4][2], const Unit& u, int wr, int wc, int fr, int fq) const {
;         const int row0 = u.pm * BM + wr * 64 + fr, col0 = u.pn * BM + wc * 32 + 8 * fq;
; #pragma unroll
;         for (int ai = 0; ai < 2; ++ai)
; #pragma unroll
;             for (int m = 0; m < 4; ++m) { const int row = row0 + ai * HALF + m * 16;
; #pragma unroll
;                 for (int bj = 0; bj < 2; ++bj) { const int col = col0 + bj * HALF;
;                     const u32x4 gp = *(const u32x4*)(proj + (size_t)row * NPROJ + C_GP + col);
;                     f32x4 f0 = (f32x4){bflo(gp.x), bfhi(gp.x), bflo(gp.y), bfhi(gp.y)}, f1 = (f32x4){bflo(gp.z), bfhi(gp.z), bflo(gp.w), bfhi(gp.w)};
;                     if (which == 0) { const u32x4 r = *(const u32x4*)(proj + (size_t)row * NPROJ + C_GS + col);
;                         f0 *= (f32x4){bflo(r.x), bfhi(r.x), bflo(r.y), bfhi(r.y)}; f1 *= (f32x4){bflo(r.z), bfhi(r.z), bflo(r.w), bfhi(r.w)}; }
;                     float* d = F + (size_t)(row - 8192) * DM + col;
;                     *(f32x4*)d = acc[ai][bj][m][0] * f0; *(f32x4*)(d + 4) = acc[ai][bj][m][1] * f1; } }
;     }
.LBB0_869:
	v_pk_mul_f32 v[52:53], v[52:53], v[60:61]
	v_pk_mul_f32 v[50:51], v[50:51], v[58:59]
	global_store_dwordx4 v[68:69], v[50:53], off offset:528
	v_pk_mul_f32 v[56:57], v[56:57], v[64:65]
	v_pk_mul_f32 v[54:55], v[54:55], v[62:63]
	v_add_u32_e32 v52, 0x90, v142
	v_mov_b64_e32 v[50:51], s[92:93]
	v_mad_i64_i32 v[50:51], s[24:25], v52, s91, v[50:51]
	global_store_dwordx4 v[68:69], v[54:57], off offset:512
	s_and_b64 vcc, exec, s[36:37]
	s_nop 0
	v_lshl_add_u64 v[54:55], v[50:51], 0, s[76:77]
	v_lshl_add_u64 v[52:53], v[140:141], 1, v[54:55]
	s_waitcnt vmcnt(25)
	v_mov_b32_e32 v56, v228
	v_mov_b32_e32 v57, v229
	v_mov_b32_e32 v58, v230
	v_mov_b32_e32 v59, v231
	v_lshlrev_b32_e32 v60, 16, v56
	v_and_b32_e32 v61, 0xffff0000, v56
	v_lshlrev_b32_e32 v62, 16, v57
	v_and_b32_e32 v63, 0xffff0000, v57
	v_lshlrev_b32_e32 v56, 16, v58
	v_and_b32_e32 v57, 0xffff0000, v58
	v_lshlrev_b32_e32 v58, 16, v59
	v_and_b32_e32 v59, 0xffff0000, v59
	s_cbranch_vccnz .LBB0_871
	v_lshl_add_u64 v[52:53], v[140:141], 1, v[50:51]
	v_add_co_u32_e32 v52, vcc, 0x4000, v52
	s_nop 1
	v_addc_co_u32_e32 v53, vcc, 0, v53, vcc
	s_waitcnt vmcnt(24)
	v_mov_b32_e32 v64, v232
	v_mov_b32_e32 v65, v233
	v_mov_b32_e32 v66, v234
	v_mov_b32_e32 v67, v235
	v_lshlrev_b32_e32 v52, 16, v64
	v_and_b32_e32 v53, 0xffff0000, v64
	v_lshlrev_b32_e32 v64, 16, v65
	v_and_b32_e32 v65, 0xffff0000, v65
	v_pk_mul_f32 v[62:63], v[62:63], v[64:65]
	v_pk_mul_f32 v[60:61], v[60:61], v[52:53]
	v_lshlrev_b32_e32 v52, 16, v66
	v_and_b32_e32 v53, 0xffff0000, v66
	v_lshlrev_b32_e32 v64, 16, v67
	v_and_b32_e32 v65, 0xffff0000, v67
	v_pk_mul_f32 v[58:59], v[58:59], v[64:65]
	v_pk_mul_f32 v[56:57], v[56:57], v[52:53]
.LBB0_871:
	v_lshlrev_b64 v[52:53], 13, v[142:143]
	v_lshl_add_u64 v[52:53], s[64:65], 0, v[52:53]
	v_lshl_add_u64 v[64:65], v[140:141], 2, v[52:53]
	s_mov_b32 s24, 0xfc120000
	s_mov_b32 s25, -1
	v_pk_mul_f32 v[46:47], v[46:47], v[60:61]
	v_add_co_u32_e32 v60, vcc, 0xfc120000, v64
	v_lshl_add_u64 v[52:53], v[64:65], 0, s[24:25]
	v_pk_mul_f32 v[48:49], v[48:49], v[62:63]
	v_addc_co_u32_e32 v61, vcc, -1, v65, vcc
	v_pk_mul_f32 v[44:45], v[44:45], v[58:59]
	v_pk_mul_f32 v[42:43], v[42:43], v[56:57]
	global_store_dwordx4 v[60:61], v[46:49], off
	global_store_dwordx4 v[52:53], v[42:45], off offset:16
	s_and_b64 vcc, exec, s[36:37]
	s_nop 0
	v_lshl_add_u64 v[42:43], v[122:123], 1, v[54:55]
	s_waitcnt vmcnt(23)
	v_mov_b32_e32 v42, v236
	v_mov_b32_e32 v43, v237
	v_mov_b32_e32 v44, v238
	v_mov_b32_e32 v45, v239
	v_lshlrev_b32_e32 v46, 16, v42
	v_and_b32_e32 v47, 0xffff0000, v42
	v_lshlrev_b32_e32 v48, 16, v43
	v_and_b32_e32 v49, 0xffff0000, v43
	v_lshlrev_b32_e32 v42, 16, v44
	v_and_b32_e32 v43, 0xffff0000, v44
	v_lshlrev_b32_e32 v44, 16, v45
	v_and_b32_e32 v45, 0xffff0000, v45
	s_cbranch_vccnz .LBB0_873
	v_lshl_add_u64 v[50:51], v[122:123], 1, v[50:51]
	v_add_co_u32_e32 v50, vcc, 0x4000, v50
	s_nop 1
	v_addc_co_u32_e32 v51, vcc, 0, v51, vcc
	s_waitcnt vmcnt(22)
	v_mov_b32_e32 v54, v180
	v_mov_b32_e32 v55, v181
	v_mov_b32_e32 v56, v182
	v_mov_b32_e32 v57, v183
	v_lshlrev_b32_e32 v50, 16, v54
	v_and_b32_e32 v51, 0xffff0000, v54
	v_lshlrev_b32_e32 v54, 16, v55
	v_and_b32_e32 v55, 0xffff0000, v55
	v_pk_mul_f32 v[48:49], v[48:49], v[54:55]
	v_pk_mul_f32 v[46:47], v[46:47], v[50:51]
	v_lshlrev_b32_e32 v50, 16, v56
	v_and_b32_e32 v51, 0xffff0000, v56
	v_lshlrev_b32_e32 v54, 16, v57
	v_and_b32_e32 v55, 0xffff0000, v57
	v_pk_mul_f32 v[44:45], v[44:45], v[54:55]
	v_pk_mul_f32 v[42:43], v[42:43], v[50:51]
.LBB0_873:
	v_pk_mul_f32 v[36:37], v[36:37], v[44:45]
	v_pk_mul_f32 v[34:35], v[34:35], v[42:43]
	global_store_dwordx4 v[52:53], v[34:37], off offset:528
	v_pk_mul_f32 v[40:41], v[40:41], v[48:49]
	v_pk_mul_f32 v[38:39], v[38:39], v[46:47]
	v_add_u32_e32 v36, 0xa0, v142
	v_mov_b64_e32 v[34:35], s[92:93]
	v_mad_i64_i32 v[34:35], s[24:25], v36, s91, v[34:35]
	global_store_dwordx4 v[52:53], v[38:41], off offset:512
	s_and_b64 vcc, exec, s[36:37]
	s_nop 0
	v_lshl_add_u64 v[38:39], v[34:35], 0, s[76:77]
	v_lshl_add_u64 v[36:37], v[140:141], 1, v[38:39]
	s_waitcnt vmcnt(21)
	v_mov_b32_e32 v40, v184
	v_mov_b32_e32 v41, v185
	v_mov_b32_e32 v42, v186
	v_mov_b32_e32 v43, v187
	v_lshlrev_b32_e32 v44, 16, v40
	v_and_b32_e32 v45, 0xffff0000, v40
	v_lshlrev_b32_e32 v46, 16, v41
	v_and_b32_e32 v47, 0xffff0000, v41
	v_lshlrev_b32_e32 v40, 16, v42
	v_and_b32_e32 v41, 0xffff0000, v42
	v_lshlrev_b32_e32 v42, 16, v43
	v_and_b32_e32 v43, 0xffff0000, v43
	s_cbranch_vccnz .LBB0_875
	v_lshl_add_u64 v[36:37], v[140:141], 1, v[34:35]
	v_add_co_u32_e32 v36, vcc, 0x4000, v36
	s_nop 1
	v_addc_co_u32_e32 v37, vcc, 0, v37, vcc
	s_waitcnt vmcnt(20)
	v_mov_b32_e32 v48, v188
	v_mov_b32_e32 v49, v189
	v_mov_b32_e32 v50, v190
	v_mov_b32_e32 v51, v191
	v_lshlrev_b32_e32 v36, 16, v48
	v_and_b32_e32 v37, 0xffff0000, v48
	v_lshlrev_b32_e32 v48, 16, v49
	v_and_b32_e32 v49, 0xffff0000, v49
	v_pk_mul_f32 v[46:47], v[46:47], v[48:49]
	v_pk_mul_f32 v[44:45], v[44:45], v[36:37]
	v_lshlrev_b32_e32 v36, 16, v50
	v_and_b32_e32 v37, 0xffff0000, v50
	v_lshlrev_b32_e32 v48, 16, v51
	v_and_b32_e32 v49, 0xffff0000, v51
	v_pk_mul_f32 v[42:43], v[42:43], v[48:49]
	v_pk_mul_f32 v[40:41], v[40:41], v[36:37]
; __device__ __forceinline__ float bflo(unsigned w) { return __uint_as_float(w << 16); }
; __device__ __forceinline__ float bfhi(unsigned w) { return __uint_as_float(w & 0xffff0000u); }
;     __device__ __forceinline__ void operator()(const f32x4 (&acc)[2][2][4][2], const Unit& u, int wr, int wc, int fr, int fq) const {
;         const int row0 = u.pm * BM + wr * 64 + fr, col0 = u.pn * BM + wc * 32 + 8 * fq;
; #pragma unroll
;         for (int ai = 0; ai < 2; ++ai)
; #pragma unroll
;             for (int m = 0; m < 4; ++m) { const int row = row0 + ai * HALF + m * 16;
; #pragma unroll
;                 for (int bj = 0; bj < 2; ++bj) { const int col = col0 + bj * HALF;
;                     const u32x4 gp = *(const u32x4*)(proj + (size_t)row * NPROJ + C_GP + col);
;                     f32x4 f0 = (f32x4){bflo(gp.x), bfhi(gp.x), bflo(gp.y), bfhi(gp.y)}, f1 = (f32x4){bflo(gp.z), bfhi(gp.z), bflo(gp.w), bfhi(gp.w)};
;                     if (which == 0) { const u32x4 r = *(const u32x4*)(proj + (size_t)row * NPROJ + C_GS + col);
;                         f0 *= (f32x4){bflo(r.x), bfhi(r.x), bflo(r.y), bfhi(r.y)}; f1 *= (f32x4){bflo(r.z), bfhi(r.z), bflo(r.w), bfhi(r.w)}; }
;                     float* d = F + (size_t)(row - 8192) * DM + col;
;                     *(f32x4*)d = acc[ai][bj][m][0] * f0; *(f32x4*)(d + 4) = acc[ai][bj][m][1] * f1; } }
;     }
.LBB0_875:
	v_lshlrev_b64 v[36:37], 13, v[142:143]
	v_lshl_add_u64 v[36:37], s[64:65], 0, v[36:37]
	v_lshl_add_u64 v[48:49], v[140:141], 2, v[36:37]
	s_mov_b32 s24, 0xfc140000
	s_mov_b32 s25, -1
	v_pk_mul_f32 v[30:31], v[30:31], v[44:45]
	v_add_co_u32_e32 v44, vcc, 0xfc140000, v48
	v_lshl_add_u64 v[36:37], v[48:49], 0, s[24:25]
	v_pk_mul_f32 v[32:33], v[32:33], v[46:47]
	v_addc_co_u32_e32 v45, vcc, -1, v49, vcc
	v_pk_mul_f32 v[28:29], v[28:29], v[42:43]
	v_pk_mul_f32 v[26:27], v[26:27], v[40:41]
	global_store_dwordx4 v[44:45], v[30:33], off
	global_store_dwordx4 v[36:37], v[26:29], off offset:16
	s_and_b64 vcc, exec, s[36:37]
	s_nop 0
	v_lshl_add_u64 v[26:27], v[122:123], 1, v[38:39]
	s_waitcnt vmcnt(19)
	v_mov_b32_e32 v26, v166
	v_mov_b32_e32 v27, v167
	v_mov_b32_e32 v28, v168
	v_mov_b32_e32 v29, v169
	v_lshlrev_b32_e32 v30, 16, v26
	v_and_b32_e32 v31, 0xffff0000, v26
	v_lshlrev_b32_e32 v32, 16, v27
	v_and_b32_e32 v33, 0xffff0000, v27
	v_lshlrev_b32_e32 v26, 16, v28
	v_and_b32_e32 v27, 0xffff0000, v28
	v_lshlrev_b32_e32 v28, 16, v29
	v_and_b32_e32 v29, 0xffff0000, v29
	s_cbranch_vccnz .LBB0_877
	v_lshl_add_u64 v[34:35], v[122:123], 1, v[34:35]
	v_add_co_u32_e32 v34, vcc, 0x4000, v34
	s_nop 1
	v_addc_co_u32_e32 v35, vcc, 0, v35, vcc
	s_waitcnt vmcnt(18)
	v_mov_b32_e32 v38, v246
	v_mov_b32_e32 v39, v247
	v_mov_b32_e32 v40, v248
	v_mov_b32_e32 v41, v249
	v_lshlrev_b32_e32 v34, 16, v38
	v_and_b32_e32 v35, 0xffff0000, v38
	v_lshlrev_b32_e32 v38, 16, v39
	v_and_b32_e32 v39, 0xffff0000, v39
	v_pk_mul_f32 v[32:33], v[32:33], v[38:39]
	v_pk_mul_f32 v[30:31], v[30:31], v[34:35]
	v_lshlrev_b32_e32 v34, 16, v40
	v_and_b32_e32 v35, 0xffff0000, v40
	v_lshlrev_b32_e32 v38, 16, v41
	v_and_b32_e32 v39, 0xffff0000, v41
	v_pk_mul_f32 v[28:29], v[28:29], v[38:39]
	v_pk_mul_f32 v[26:27], v[26:27], v[34:35]
.LBB0_877:
	v_pk_mul_f32 v[20:21], v[20:21], v[28:29]
	v_pk_mul_f32 v[18:19], v[18:19], v[26:27]
	global_store_dwordx4 v[36:37], v[18:21], off offset:528
	v_pk_mul_f32 v[24:25], v[24:25], v[32:33]
	v_pk_mul_f32 v[22:23], v[22:23], v[30:31]
	v_add_u32_e32 v20, 0xb0, v142
	v_mov_b64_e32 v[18:19], s[92:93]
	v_mad_i64_i32 v[18:19], s[24:25], v20, s91, v[18:19]
	global_store_dwordx4 v[36:37], v[22:25], off offset:512
	s_and_b64 vcc, exec, s[36:37]
	s_nop 0
	v_lshl_add_u64 v[22:23], v[18:19], 0, s[76:77]
	v_lshl_add_u64 v[20:21], v[140:141], 1, v[22:23]
	s_waitcnt vmcnt(17)
	v_mov_b32_e32 v24, v204
	v_mov_b32_e32 v25, v205
	v_mov_b32_e32 v26, v206
	v_mov_b32_e32 v27, v207
	v_lshlrev_b32_e32 v28, 16, v24
	v_and_b32_e32 v29, 0xffff0000, v24
	v_lshlrev_b32_e32 v30, 16, v25
	v_and_b32_e32 v31, 0xffff0000, v25
	v_lshlrev_b32_e32 v24, 16, v26
	v_and_b32_e32 v25, 0xffff0000, v26
	v_lshlrev_b32_e32 v26, 16, v27
	v_and_b32_e32 v27, 0xffff0000, v27
	s_cbranch_vccnz .LBB0_879
	v_lshl_add_u64 v[20:21], v[140:141], 1, v[18:19]
	v_add_co_u32_e32 v20, vcc, 0x4000, v20
	s_nop 1
	v_addc_co_u32_e32 v21, vcc, 0, v21, vcc
	s_waitcnt vmcnt(16)
	v_mov_b32_e32 v32, v208
	v_mov_b32_e32 v33, v209
	v_mov_b32_e32 v34, v210
	v_mov_b32_e32 v35, v211
	v_lshlrev_b32_e32 v20, 16, v32
	v_and_b32_e32 v21, 0xffff0000, v32
	v_lshlrev_b32_e32 v32, 16, v33
	v_and_b32_e32 v33, 0xffff0000, v33
	v_pk_mul_f32 v[30:31], v[30:31], v[32:33]
	v_pk_mul_f32 v[28:29], v[28:29], v[20:21]
	v_lshlrev_b32_e32 v20, 16, v34
	v_and_b32_e32 v21, 0xffff0000, v34
	v_lshlrev_b32_e32 v32, 16, v35
	v_and_b32_e32 v33, 0xffff0000, v35
	v_pk_mul_f32 v[26:27], v[26:27], v[32:33]
	v_pk_mul_f32 v[24:25], v[24:25], v[20:21]
.LBB0_879:
	v_lshlrev_b64 v[20:21], 13, v[142:143]
	v_lshl_add_u64 v[20:21], s[64:65], 0, v[20:21]
	v_lshl_add_u64 v[32:33], v[140:141], 2, v[20:21]
	s_mov_b32 s24, 0xfc160000
	s_mov_b32 s25, -1
	v_pk_mul_f32 v[14:15], v[14:15], v[28:29]
	v_add_co_u32_e32 v28, vcc, 0xfc160000, v32
	v_lshl_add_u64 v[20:21], v[32:33], 0, s[24:25]
	v_pk_mul_f32 v[16:17], v[16:17], v[30:31]
	v_addc_co_u32_e32 v29, vcc, -1, v33, vcc
	v_pk_mul_f32 v[12:13], v[12:13], v[26:27]
	v_pk_mul_f32 v[10:11], v[10:11], v[24:25]
	global_store_dwordx4 v[28:29], v[14:17], off
	global_store_dwordx4 v[20:21], v[10:13], off offset:16
	s_and_b64 vcc, exec, s[36:37]
	s_nop 0
	v_lshl_add_u64 v[10:11], v[122:123], 1, v[22:23]
	s_waitcnt vmcnt(15)
	v_mov_b32_e32 v10, v212
	v_mov_b32_e32 v11, v213
	v_mov_b32_e32 v12, v214
	v_mov_b32_e32 v13, v215
	v_lshlrev_b32_e32 v14, 16, v10
	v_and_b32_e32 v15, 0xffff0000, v10
	v_lshlrev_b32_e32 v16, 16, v11
	v_and_b32_e32 v17, 0xffff0000, v11
	v_lshlrev_b32_e32 v10, 16, v12
	v_and_b32_e32 v11, 0xffff0000, v12
	v_lshlrev_b32_e32 v12, 16, v13
	v_and_b32_e32 v13, 0xffff0000, v13
	s_cbranch_vccnz .LBB0_844
	v_lshl_add_u64 v[18:19], v[122:123], 1, v[18:19]
	v_add_co_u32_e32 v18, vcc, 0x4000, v18
	s_nop 1
	v_addc_co_u32_e32 v19, vcc, 0, v19, vcc
	s_waitcnt vmcnt(14)
	v_mov_b32_e32 v22, v216
	v_mov_b32_e32 v23, v217
	v_mov_b32_e32 v24, v218
	v_mov_b32_e32 v25, v219
	v_lshlrev_b32_e32 v18, 16, v22
	v_and_b32_e32 v19, 0xffff0000, v22
	v_lshlrev_b32_e32 v22, 16, v23
	v_and_b32_e32 v23, 0xffff0000, v23
	v_pk_mul_f32 v[16:17], v[16:17], v[22:23]
	v_pk_mul_f32 v[14:15], v[14:15], v[18:19]
	v_lshlrev_b32_e32 v18, 16, v24
	v_and_b32_e32 v19, 0xffff0000, v24
	v_lshlrev_b32_e32 v22, 16, v25
	v_and_b32_e32 v23, 0xffff0000, v25
	v_pk_mul_f32 v[12:13], v[12:13], v[22:23]
	v_pk_mul_f32 v[10:11], v[10:11], v[18:19]
	s_branch .LBB0_844
